# conv loop 422 LDS refill reorder with counted lgkmcnt waits; attention K-row sum of squares all-reduce via DPP instead of 4 ds_bpermute hops
# baseline (speedup 1.0000x reference)
; #define CONV_TAIL() if (step + CONV_GRP < nsteps) CONV_STOREWIN(step + CONV_GRP); if ((step & 1) == 1 || step + 1 == nsteps) __syncthreads()
; #define CONV_DS(x) ({ int t_ = (x); LAUNDER_S(t_); t_; })
; #define CONV_NB1(H) ((d + 1 <= hi0) ? CONV_BPH(0, H, d + 1) : CONV_BPH(1, H, d + 1))
; __device__ __forceinline__ void conv_item(const Params& P, int slice, int item, LAS unsigned char* lds) {
;     ...
;     for (int d = CONV_DS(lo1 + hw); d <= hi0 - hw; ++d) { CONV_HEADT(); CONV_TILESTEP(0, CONV_BPH(1, 0, d), CONV_BPH(1, 1, d), 0, Wn, 3, 1);
;       CONV_TILESTEP(1, CONV_NB1(0), CONV_NB1(1), 1, CONV_WB(step + 1), 3, 0); CONV_TAIL(); }
.LBB0_422:
	s_add_i32 s68, s17, 1
	s_setprio 1
	v_lshl_add_u32 v240, v150, 1, v227
	global_load_dword v230, v240, s[8:9] offset:-2048
	global_load_dword v231, v240, s[8:9] offset:-1920
	global_load_dword v238, v240, s[8:9] offset:-1792
	global_load_dword v239, v240, s[8:9] offset:-1664
	v_add3_u32 v83, v247, s16, 1
	v_add3_u32 v149, v248, s16, 1
	s_add_i32 s69, s61, s17
	v_mov_b32_e32 v80, s29
	v_cmp_gt_u32_e32 vcc, s61, v83
	s_nop 1
	v_cndmask_b32_e32 v83, v80, v148, vcc
	v_cmp_gt_u32_e32 vcc, s61, v149
	s_nop 1
	v_cndmask_b32_e32 v149, v80, v82, vcc
	s_waitcnt lgkmcnt(10)
	v_mfma_f32_16x16x32_bf16 v[16:19], v[72:75], v[144:147], v[16:19]
	v_mfma_f32_16x16x32_bf16 v[20:23], v[64:67], v[144:147], v[20:23]
	v_mfma_f32_16x16x32_bf16 v[12:15], v[88:91], v[144:147], v[12:15]
	v_mfma_f32_16x16x32_bf16 v[8:11], v[76:79], v[144:147], v[8:11]
	v_mfma_f32_16x16x32_bf16 v[52:55], v[72:75], v[128:131], v[52:55]
	v_mfma_f32_16x16x32_bf16 v[48:51], v[64:67], v[128:131], v[48:51]
	v_mfma_f32_16x16x32_bf16 v[44:47], v[88:91], v[128:131], v[44:47]
	v_mfma_f32_16x16x32_bf16 v[40:43], v[76:79], v[128:131], v[40:43]
	ds_read_b128 v[144:147], v83
	ds_read_b128 v[128:131], v149
	s_waitcnt lgkmcnt(2)
	v_mfma_f32_16x16x32_bf16 v[40:43], v[64:67], v[124:127], v[40:43]
	v_mfma_f32_16x16x32_bf16 v[40:43], v[60:63], v[120:123], v[40:43]
	v_mfma_f32_16x16x32_bf16 v[40:43], v[24:27], v[116:119], v[40:43]
	v_mfma_f32_16x16x32_bf16 v[44:47], v[72:75], v[124:127], v[44:47]
	v_mfma_f32_16x16x32_bf16 v[44:47], v[56:59], v[120:123], v[44:47]
	v_mfma_f32_16x16x32_bf16 v[44:47], v[28:31], v[116:119], v[44:47]
	v_mfma_f32_16x16x32_bf16 v[48:51], v[60:63], v[124:127], v[48:51]
	v_mfma_f32_16x16x32_bf16 v[48:51], v[24:27], v[120:123], v[48:51]
	v_mfma_f32_16x16x32_bf16 v[48:51], v[36:39], v[116:119], v[48:51]
	v_mfma_f32_16x16x32_bf16 v[52:55], v[56:59], v[124:127], v[52:55]
	v_mfma_f32_16x16x32_bf16 v[52:55], v[28:31], v[120:123], v[52:55]
	v_mfma_f32_16x16x32_bf16 v[52:55], v[32:35], v[116:119], v[52:55]
	ds_read_b128 v[124:127], v149 offset:64
	ds_read_b128 v[120:123], v149 offset:128
	ds_read_b128 v[116:119], v149 offset:192
	v_mfma_f32_16x16x32_bf16 v[8:11], v[64:67], v[140:143], v[8:11]
	v_mfma_f32_16x16x32_bf16 v[16:19], v[56:59], v[140:143], v[16:19]
	v_mfma_f32_16x16x32_bf16 v[20:23], v[60:63], v[140:143], v[20:23]
	v_mfma_f32_16x16x32_bf16 v[12:15], v[72:75], v[140:143], v[12:15]
	v_mfma_f32_16x16x32_bf16 v[8:11], v[60:63], v[136:139], v[8:11]
	v_mfma_f32_16x16x32_bf16 v[8:11], v[24:27], v[132:135], v[8:11]
	v_mfma_f32_16x16x32_bf16 v[12:15], v[56:59], v[136:139], v[12:15]
	v_mfma_f32_16x16x32_bf16 v[12:15], v[28:31], v[132:135], v[12:15]
	v_mfma_f32_16x16x32_bf16 v[20:23], v[24:27], v[136:139], v[20:23]
	v_mfma_f32_16x16x32_bf16 v[20:23], v[36:39], v[132:135], v[20:23]
	v_mfma_f32_16x16x32_bf16 v[16:19], v[28:31], v[136:139], v[16:19]
	v_mfma_f32_16x16x32_bf16 v[16:19], v[32:35], v[132:135], v[16:19]
	ds_read_b128 v[140:143], v83 offset:64
	ds_read_b128 v[136:139], v83 offset:128
	ds_read_b128 v[132:135], v83 offset:192
	s_setprio 0
	s_setprio 1
	s_cmp_lt_i32 s68, s26
	s_cselect_b64 vcc, -1, 0
	v_cndmask_b32_e32 v83, v247, v242, vcc
	v_add_u32_e32 v83, s16, v83
	v_cndmask_b32_e32 v149, v248, v245, vcc
	v_cmp_gt_u32_e64 s[0:1], s61, v83
	v_mad_u64_u32 v[152:153], s[70:71], v83, s85, v[156:157]
	v_add_u32_e32 v149, s16, v149
	v_cndmask_b32_e64 v83, v80, v152, s[0:1]
	v_mad_u64_u32 v[152:153], s[0:1], v149, s85, v[156:157]
	s_add_i32 s0, s69, 1
	s_and_b32 s0, s0, 7
	v_cmp_gt_u32_e32 vcc, s61, v149
	s_mulk_i32 s0, 0x1200
	v_add_u32_e32 v149, s0, v243
	v_cndmask_b32_e32 v80, v80, v152, vcc
	s_waitcnt lgkmcnt(6)
	v_mfma_f32_16x16x32_bf16 v[92:95], v[72:75], v[144:147], v[92:95]
	v_mfma_f32_16x16x32_bf16 v[96:99], v[64:67], v[144:147], v[96:99]
	v_mfma_f32_16x16x32_bf16 v[84:87], v[88:91], v[144:147], v[84:87]
	v_mfma_f32_16x16x32_bf16 v[68:71], v[76:79], v[144:147], v[68:71]
	ds_read_b128 v[144:147], v83
	v_mfma_f32_16x16x32_bf16 v[112:115], v[72:75], v[128:131], v[112:115]
	v_mfma_f32_16x16x32_bf16 v[108:111], v[64:67], v[128:131], v[108:111]
	v_mfma_f32_16x16x32_bf16 v[104:107], v[88:91], v[128:131], v[104:107]
	v_mfma_f32_16x16x32_bf16 v[100:103], v[76:79], v[128:131], v[100:103]
	ds_read_b128 v[128:131], v80
	ds_read_b128 v[76:79], v149 offset:160
	ds_read_b128 v[88:91], v149 offset:192
	s_waitcnt lgkmcnt(4)
	v_mfma_f32_16x16x32_bf16 v[92:95], v[56:59], v[140:143], v[92:95]
	v_mfma_f32_16x16x32_bf16 v[96:99], v[60:63], v[140:143], v[96:99]
	v_mfma_f32_16x16x32_bf16 v[84:87], v[72:75], v[140:143], v[84:87]
	v_mfma_f32_16x16x32_bf16 v[68:71], v[64:67], v[140:143], v[68:71]
	ds_read_b128 v[140:143], v83 offset:64
	v_mfma_f32_16x16x32_bf16 v[112:115], v[56:59], v[124:127], v[112:115]
	v_mfma_f32_16x16x32_bf16 v[108:111], v[60:63], v[124:127], v[108:111]
	v_mfma_f32_16x16x32_bf16 v[104:107], v[72:75], v[124:127], v[104:107]
	v_mfma_f32_16x16x32_bf16 v[100:103], v[64:67], v[124:127], v[100:103]
	ds_read_b128 v[124:127], v80 offset:64
	ds_read_b128 v[64:67], v149 offset:224
	ds_read_b128 v[72:75], v149 offset:256
	v_mfma_f32_16x16x32_bf16 v[92:95], v[28:31], v[136:139], v[92:95]
	v_mfma_f32_16x16x32_bf16 v[96:99], v[24:27], v[136:139], v[96:99]
	v_mfma_f32_16x16x32_bf16 v[84:87], v[56:59], v[136:139], v[84:87]
	v_mfma_f32_16x16x32_bf16 v[68:71], v[60:63], v[136:139], v[68:71]
	ds_read_b128 v[136:139], v83 offset:128
	v_mfma_f32_16x16x32_bf16 v[112:115], v[28:31], v[120:123], v[112:115]
	v_mfma_f32_16x16x32_bf16 v[108:111], v[24:27], v[120:123], v[108:111]
	v_mfma_f32_16x16x32_bf16 v[104:107], v[56:59], v[120:123], v[104:107]
	v_mfma_f32_16x16x32_bf16 v[100:103], v[60:63], v[120:123], v[100:103]
	ds_read_b128 v[120:123], v80 offset:128
	ds_read_b128 v[60:63], v149 offset:288
	ds_read_b128 v[56:59], v149 offset:320
	v_mfma_f32_16x16x32_bf16 v[92:95], v[32:35], v[132:135], v[92:95]
	v_mfma_f32_16x16x32_bf16 v[96:99], v[36:39], v[132:135], v[96:99]
	v_mfma_f32_16x16x32_bf16 v[84:87], v[28:31], v[132:135], v[84:87]
	v_mfma_f32_16x16x32_bf16 v[68:71], v[24:27], v[132:135], v[68:71]
	ds_read_b128 v[132:135], v83 offset:192
	v_mfma_f32_16x16x32_bf16 v[112:115], v[32:35], v[116:119], v[112:115]
	v_mfma_f32_16x16x32_bf16 v[108:111], v[36:39], v[116:119], v[108:111]
	v_mfma_f32_16x16x32_bf16 v[104:107], v[28:31], v[116:119], v[104:107]
	v_mfma_f32_16x16x32_bf16 v[100:103], v[24:27], v[116:119], v[100:103]
	ds_read_b128 v[116:119], v80 offset:192
	ds_read_b128 v[24:27], v149 offset:352
	ds_read_b128 v[28:31], v149 offset:384
	ds_read_b128 v[36:39], v149 offset:416
	ds_read_b128 v[32:35], v149 offset:448
	s_setprio 0
	s_add_i32 s0, s69, 4
	s_cmp_ge_i32 s0, s87
	s_cbranch_scc1 .LBB0_424
	s_and_b32 s0, s0, 4
	s_and_b32 s1, s69, 3
	s_or_b32 s0, s0, s1
	s_mulk_i32 s0, 0x1200
	v_add_u32_e32 v80, s0, v157
	s_waitcnt vmcnt(0)
	ds_write2_b32 v80, v230, v231 offset1:32
	ds_write2_b32 v80, v238, v239 offset0:64 offset1:96

; #define LAS __attribute__((address_space(3)))
; #define LAUNDER_V(x) asm volatile("" : "+v"(x))
; __device__ __forceinline__ unsigned pk2(float lo, float hi) { const f32x2_t f = {lo, hi}; const bf16x2_t b = __builtin_convertvector(f, bf16x2_t); return __builtin_bit_cast(unsigned, b); }
; __device__ __forceinline__ float lo16(unsigned v) { return __uint_as_float(v << 16); }
; __device__ __forceinline__ float hi16(unsigned v) { return __uint_as_float(v & 0xffff0000u); }
; __device__ __forceinline__ void stage_kv(const u16* src_base_  , int b, int L, int dil, int r, int m0, int M, LAS unsigned char* img, const float* gk, int ht) {
;     ...
;     if (!valid) { v.x = 0u; LAUNDER_V(v.x); v.y = v.x; v.z = v.x; v.w = v.x; }
;     if (gk) {
;       float f[8] = {lo16(v.x), hi16(v.x), lo16(v.y), hi16(v.y), lo16(v.z), hi16(v.z), lo16(v.w), hi16(v.w)};
;       float s = 0.f;
; #pragma unroll
;       for (int e = 0; e < 8; ++e) s += f[e] * f[e];
;       s += __shfl_xor(s, 1); s += __shfl_xor(s, 2); s += __shfl_xor(s, 4); s += __shfl_xor(s, 8);
;       const float rs = rsqrtf(s * (1.0f / 128.0f) + 1e-6f);
;       v.x = pk2(f[0] * rs * gv[0], f[1] * rs * gv[1]); v.y = pk2(f[2] * rs * gv[2], f[3] * rs * gv[3]);
;       v.z = pk2(f[4] * rs * gv[4], f[5] * rs * gv[5]); v.w = pk2(f[6] * rs * gv[6], f[7] * rs * gv[7]);
;     }
;     *(LAS u32x4*)(img + kl * KROW + dch * 16) = v;
.LBB0_531:
	s_or_b64 exec, exec, s[8:9]
	v_readlane_b32 s8, v253, 23
	v_readlane_b32 s9, v253, 24
	v_mov_b32_e32 v69, v72
	s_and_b64 vcc, exec, s[8:9]
	s_cbranch_vccz .LBB0_624
	v_lshlrev_b32_e32 v88, 16, v68
	v_and_b32_e32 v89, 0xffff0000, v68
	v_lshlrev_b32_e32 v84, 16, v69
	v_and_b32_e32 v85, 0xffff0000, v69
	v_pk_mul_f32 v[90:91], v[88:89], v[88:89]
	v_and_b32_e32 v73, 64, v225
	v_pk_mul_f32 v[86:87], v[84:85], v[84:85]
	v_add_f32_e32 v90, v90, v91
	v_xor_b32_e32 v72, 1, v225
	v_add_u32_e32 v92, 64, v73
	v_lshlrev_b32_e32 v74, 16, v70
	v_and_b32_e32 v75, 0xffff0000, v70
	v_add_f32_e32 v86, v86, v90
	v_cmp_lt_i32_e32 vcc, v72, v92
	v_pk_mul_f32 v[82:83], v[74:75], v[74:75]
	v_add_f32_e32 v86, v87, v86
	v_cndmask_b32_e32 v72, v225, v72, vcc
	v_lshlrev_b32_e32 v78, 16, v71
	v_and_b32_e32 v79, 0xffff0000, v71
	v_add_f32_e32 v82, v82, v86
	v_lshlrev_b32_e32 v93, 2, v72
	v_pk_mul_f32 v[72:73], v[78:79], v[78:79]
	v_add_f32_e32 v82, v83, v82
	v_add_f32_e32 v72, v72, v82
	v_add_f32_e32 v72, v73, v72
	s_mov_b32 s8, 0x800000
	s_nop 1
	v_add_f32_dpp v72, v72, v72 quad_perm:[1,0,3,2] row_mask:0xf bank_mask:0xf
	s_nop 1
	v_add_f32_dpp v72, v72, v72 quad_perm:[2,3,0,1] row_mask:0xf bank_mask:0xf
	s_nop 1
	v_add_f32_dpp v72, v72, v72 row_half_mirror row_mask:0xf bank_mask:0xf
	s_nop 1
	v_add_f32_dpp v72, v72, v72 row_mirror row_mask:0xf bank_mask:0xf
	v_fmamk_f32 v72, v72, 0x3c000000, v218
	v_mul_f32_e32 v73, 0x4b800000, v72
	v_cmp_gt_f32_e32 vcc, s8, v72
	s_nop 1
	v_cndmask_b32_e32 v72, v72, v73, vcc
	v_rsq_f32_e32 v72, v72
	s_nop 0
	v_mul_f32_e32 v73, 0x45800000, v72
	v_cndmask_b32_e32 v82, v72, v73, vcc
	v_pk_mul_f32 v[72:73], v[82:83], v[88:89] op_sel_hi:[0,1]
	v_pk_mul_f32 v[84:85], v[82:83], v[84:85] op_sel_hi:[0,1]
	v_pk_mul_f32 v[74:75], v[82:83], v[74:75] op_sel_hi:[0,1]
	v_pk_mul_f32 v[78:79], v[82:83], v[78:79] op_sel_hi:[0,1]
	s_waitcnt vmcnt(0)
	v_pk_mul_f32 v[72:73], v[4:5], v[72:73]
	v_pk_mul_f32 v[84:85], v[6:7], v[84:85]
	v_pk_mul_f32 v[74:75], v[0:1], v[74:75]
	v_pk_mul_f32 v[78:79], v[2:3], v[78:79]
	v_cvt_pk_bf16_f32 v72, v72, v73
	v_cvt_pk_bf16_f32 v73, v84, v85
	v_cvt_pk_bf16_f32 v74, v74, v75
	v_cvt_pk_bf16_f32 v75, v78, v79
	s_cbranch_execnz .LBB0_534

; #define LAS __attribute__((address_space(3)))
; #define LAUNDER_V(x) asm volatile("" : "+v"(x))
; __device__ __forceinline__ unsigned pk2(float lo, float hi) { const f32x2_t f = {lo, hi}; const bf16x2_t b = __builtin_convertvector(f, bf16x2_t); return __builtin_bit_cast(unsigned, b); }
; __device__ __forceinline__ float lo16(unsigned v) { return __uint_as_float(v << 16); }
; __device__ __forceinline__ float hi16(unsigned v) { return __uint_as_float(v & 0xffff0000u); }
; __device__ __forceinline__ void stage_kv(const u16* src_base_  , int b, int L, int dil, int r, int m0, int M, LAS unsigned char* img, const float* gk, int ht) {
;     ...
;     if (!valid) { v.x = 0u; LAUNDER_V(v.x); v.y = v.x; v.z = v.x; v.w = v.x; }
;     if (gk) {
;       float f[8] = {lo16(v.x), hi16(v.x), lo16(v.y), hi16(v.y), lo16(v.z), hi16(v.z), lo16(v.w), hi16(v.w)};
;       float s = 0.f;
; #pragma unroll
;       for (int e = 0; e < 8; ++e) s += f[e] * f[e];
;       s += __shfl_xor(s, 1); s += __shfl_xor(s, 2); s += __shfl_xor(s, 4); s += __shfl_xor(s, 8);
;       const float rs = rsqrtf(s * (1.0f / 128.0f) + 1e-6f);
;       v.x = pk2(f[0] * rs * gv[0], f[1] * rs * gv[1]); v.y = pk2(f[2] * rs * gv[2], f[3] * rs * gv[3]);
;       v.z = pk2(f[4] * rs * gv[4], f[5] * rs * gv[5]); v.w = pk2(f[6] * rs * gv[6], f[7] * rs * gv[7]);
;     }
;     *(LAS u32x4*)(img + kl * KROW + dch * 16) = v;
.LBB0_536:
	s_or_saveexec_b64 s[8:9], s[8:9]
	s_waitcnt vmcnt(0)
	v_mov_b32_e32 v70, v65
	v_mov_b32_e32 v71, v65
	s_xor_b64 exec, exec, s[8:9]
	v_mov_b64_e32 v[70:71], v[66:67]
	v_mov_b64_e32 v[68:69], v[64:65]
	s_or_b64 exec, exec, s[8:9]
	v_readlane_b32 s8, v253, 23
	v_readlane_b32 s9, v253, 24
	v_mov_b32_e32 v69, v65
	s_and_b64 vcc, exec, s[8:9]
	s_cbranch_vccz .LBB0_625
	v_lshlrev_b32_e32 v84, 16, v68
	v_and_b32_e32 v85, 0xffff0000, v68
	v_lshlrev_b32_e32 v78, 16, v69
	v_and_b32_e32 v79, 0xffff0000, v69
	v_pk_mul_f32 v[86:87], v[84:85], v[84:85]
	v_and_b32_e32 v65, 64, v225
	v_pk_mul_f32 v[82:83], v[78:79], v[78:79]
	v_add_f32_e32 v86, v86, v87
	v_xor_b32_e32 v64, 1, v225
	v_add_u32_e32 v88, 64, v65
	v_lshlrev_b32_e32 v66, 16, v70
	v_and_b32_e32 v67, 0xffff0000, v70
	v_add_f32_e32 v82, v82, v86
	v_cmp_lt_i32_e32 vcc, v64, v88
	v_pk_mul_f32 v[74:75], v[66:67], v[66:67]
	v_add_f32_e32 v82, v83, v82
	v_cndmask_b32_e32 v64, v225, v64, vcc
	v_lshlrev_b32_e32 v72, 16, v71
	v_and_b32_e32 v73, 0xffff0000, v71
	v_add_f32_e32 v74, v74, v82
	v_lshlrev_b32_e32 v89, 2, v64
	v_pk_mul_f32 v[64:65], v[72:73], v[72:73]
	v_add_f32_e32 v74, v75, v74
	v_add_f32_e32 v64, v64, v74
	v_add_f32_e32 v64, v65, v64
	s_mov_b32 s8, 0x800000
	s_nop 1
	v_add_f32_dpp v64, v64, v64 quad_perm:[1,0,3,2] row_mask:0xf bank_mask:0xf
	s_nop 1
	v_add_f32_dpp v64, v64, v64 quad_perm:[2,3,0,1] row_mask:0xf bank_mask:0xf
	s_nop 1
	v_add_f32_dpp v64, v64, v64 row_half_mirror row_mask:0xf bank_mask:0xf
	s_nop 1
	v_add_f32_dpp v64, v64, v64 row_mirror row_mask:0xf bank_mask:0xf
	v_fmamk_f32 v64, v64, 0x3c000000, v218
	v_mul_f32_e32 v65, 0x4b800000, v64
	v_cmp_gt_f32_e32 vcc, s8, v64
	s_nop 1
	v_cndmask_b32_e32 v64, v64, v65, vcc
	v_rsq_f32_e32 v64, v64
	s_nop 0
	v_mul_f32_e32 v65, 0x45800000, v64
	v_cndmask_b32_e32 v74, v64, v65, vcc
	v_pk_mul_f32 v[64:65], v[74:75], v[84:85] op_sel_hi:[0,1]
	v_pk_mul_f32 v[78:79], v[74:75], v[78:79] op_sel_hi:[0,1]
	v_pk_mul_f32 v[66:67], v[74:75], v[66:67] op_sel_hi:[0,1]
	v_pk_mul_f32 v[72:73], v[74:75], v[72:73] op_sel_hi:[0,1]
	v_pk_mul_f32 v[64:65], v[4:5], v[64:65]
	v_pk_mul_f32 v[78:79], v[6:7], v[78:79]
	v_pk_mul_f32 v[66:67], v[0:1], v[66:67]
	v_pk_mul_f32 v[72:73], v[2:3], v[72:73]
	v_cvt_pk_bf16_f32 v64, v64, v65
	v_cvt_pk_bf16_f32 v65, v78, v79
	v_cvt_pk_bf16_f32 v66, v66, v67
	v_cvt_pk_bf16_f32 v67, v72, v73
	s_cbranch_execnz .LBB0_541

; #define LAS __attribute__((address_space(3)))
; #define LAUNDER_V(x) asm volatile("" : "+v"(x))
; __device__ __forceinline__ unsigned pk2(float lo, float hi) { const f32x2_t f = {lo, hi}; const bf16x2_t b = __builtin_convertvector(f, bf16x2_t); return __builtin_bit_cast(unsigned, b); }
; __device__ __forceinline__ float lo16(unsigned v) { return __uint_as_float(v << 16); }
; __device__ __forceinline__ float hi16(unsigned v) { return __uint_as_float(v & 0xffff0000u); }
; __device__ __forceinline__ void stage_kv(const u16* src_base_  , int b, int L, int dil, int r, int m0, int M, LAS unsigned char* img, const float* gk, int ht) {
;     ...
;     if (!valid) { v.x = 0u; LAUNDER_V(v.x); v.y = v.x; v.z = v.x; v.w = v.x; }
;     if (gk) {
;       float f[8] = {lo16(v.x), hi16(v.x), lo16(v.y), hi16(v.y), lo16(v.z), hi16(v.z), lo16(v.w), hi16(v.w)};
;       float s = 0.f;
; #pragma unroll
;       for (int e = 0; e < 8; ++e) s += f[e] * f[e];
;       s += __shfl_xor(s, 1); s += __shfl_xor(s, 2); s += __shfl_xor(s, 4); s += __shfl_xor(s, 8);
;       const float rs = rsqrtf(s * (1.0f / 128.0f) + 1e-6f);
;       v.x = pk2(f[0] * rs * gv[0], f[1] * rs * gv[1]); v.y = pk2(f[2] * rs * gv[2], f[3] * rs * gv[3]);
;       v.z = pk2(f[4] * rs * gv[4], f[5] * rs * gv[5]); v.w = pk2(f[6] * rs * gv[6], f[7] * rs * gv[7]);
;     }
;     *(LAS u32x4*)(img + kl * KROW + dch * 16) = v;
.LBB0_543:
	s_or_saveexec_b64 s[8:9], s[8:9]
	v_mov_b32_e32 v66, v61
	v_mov_b32_e32 v67, v61
	s_xor_b64 exec, exec, s[8:9]
	v_mov_b64_e32 v[66:67], v[62:63]
	v_mov_b64_e32 v[64:65], v[60:61]
	s_or_b64 exec, exec, s[8:9]
	v_readlane_b32 s8, v253, 23
	v_readlane_b32 s9, v253, 24
	v_mov_b32_e32 v65, v61
	s_and_b64 vcc, exec, s[8:9]
	s_cbranch_vccz .LBB0_626
	v_lshlrev_b32_e32 v78, 16, v64
	v_and_b32_e32 v79, 0xffff0000, v64
	v_lshlrev_b32_e32 v72, 16, v65
	v_and_b32_e32 v73, 0xffff0000, v65
	v_pk_mul_f32 v[82:83], v[78:79], v[78:79]
	v_and_b32_e32 v61, 64, v225
	v_pk_mul_f32 v[74:75], v[72:73], v[72:73]
	v_add_f32_e32 v82, v82, v83
	v_xor_b32_e32 v60, 1, v225
	v_add_u32_e32 v77, 64, v61
	v_lshlrev_b32_e32 v62, 16, v66
	v_and_b32_e32 v63, 0xffff0000, v66
	v_add_f32_e32 v74, v74, v82
	v_cmp_lt_i32_e32 vcc, v60, v77
	v_pk_mul_f32 v[70:71], v[62:63], v[62:63]
	v_add_f32_e32 v74, v75, v74
	v_cndmask_b32_e32 v60, v225, v60, vcc
	v_lshlrev_b32_e32 v68, 16, v67
	v_and_b32_e32 v69, 0xffff0000, v67
	v_add_f32_e32 v70, v70, v74
	v_lshlrev_b32_e32 v84, 2, v60
	v_pk_mul_f32 v[60:61], v[68:69], v[68:69]
	v_add_f32_e32 v70, v71, v70
	v_add_f32_e32 v60, v60, v70
	v_add_f32_e32 v60, v61, v60
	s_mov_b32 s8, 0x800000
	s_nop 1
	v_add_f32_dpp v60, v60, v60 quad_perm:[1,0,3,2] row_mask:0xf bank_mask:0xf
	s_nop 1
	v_add_f32_dpp v60, v60, v60 quad_perm:[2,3,0,1] row_mask:0xf bank_mask:0xf
	s_nop 1
	v_add_f32_dpp v60, v60, v60 row_half_mirror row_mask:0xf bank_mask:0xf
	s_nop 1
	v_add_f32_dpp v60, v60, v60 row_mirror row_mask:0xf bank_mask:0xf
	v_fmamk_f32 v60, v60, 0x3c000000, v218
	v_mul_f32_e32 v61, 0x4b800000, v60
	v_cmp_gt_f32_e32 vcc, s8, v60
	s_nop 1
	v_cndmask_b32_e32 v60, v60, v61, vcc
	v_rsq_f32_e32 v60, v60
	s_nop 0
	v_mul_f32_e32 v61, 0x45800000, v60
	v_cndmask_b32_e32 v70, v60, v61, vcc
	v_pk_mul_f32 v[60:61], v[70:71], v[78:79] op_sel_hi:[0,1]
	v_pk_mul_f32 v[72:73], v[70:71], v[72:73] op_sel_hi:[0,1]
	v_pk_mul_f32 v[62:63], v[70:71], v[62:63] op_sel_hi:[0,1]
	v_pk_mul_f32 v[68:69], v[70:71], v[68:69] op_sel_hi:[0,1]
	v_pk_mul_f32 v[60:61], v[4:5], v[60:61]
	v_pk_mul_f32 v[72:73], v[6:7], v[72:73]
	v_pk_mul_f32 v[62:63], v[0:1], v[62:63]
	v_pk_mul_f32 v[68:69], v[2:3], v[68:69]
	v_cvt_pk_bf16_f32 v60, v60, v61
	v_cvt_pk_bf16_f32 v61, v72, v73
	v_cvt_pk_bf16_f32 v62, v62, v63
	v_cvt_pk_bf16_f32 v63, v68, v69
	s_cbranch_execnz .LBB0_548

; #define LAS __attribute__((address_space(3)))
; #define LAUNDER_V(x) asm volatile("" : "+v"(x))
; __device__ __forceinline__ unsigned pk2(float lo, float hi) { const f32x2_t f = {lo, hi}; const bf16x2_t b = __builtin_convertvector(f, bf16x2_t); return __builtin_bit_cast(unsigned, b); }
; __device__ __forceinline__ float lo16(unsigned v) { return __uint_as_float(v << 16); }
; __device__ __forceinline__ float hi16(unsigned v) { return __uint_as_float(v & 0xffff0000u); }
; __device__ __forceinline__ void stage_kv(const u16* src_base_  , int b, int L, int dil, int r, int m0, int M, LAS unsigned char* img, const float* gk, int ht) {
;     ...
;     if (!valid) { v.x = 0u; LAUNDER_V(v.x); v.y = v.x; v.z = v.x; v.w = v.x; }
;     if (gk) {
;       float f[8] = {lo16(v.x), hi16(v.x), lo16(v.y), hi16(v.y), lo16(v.z), hi16(v.z), lo16(v.w), hi16(v.w)};
;       float s = 0.f;
; #pragma unroll
;       for (int e = 0; e < 8; ++e) s += f[e] * f[e];
;       s += __shfl_xor(s, 1); s += __shfl_xor(s, 2); s += __shfl_xor(s, 4); s += __shfl_xor(s, 8);
;       const float rs = rsqrtf(s * (1.0f / 128.0f) + 1e-6f);
;       v.x = pk2(f[0] * rs * gv[0], f[1] * rs * gv[1]); v.y = pk2(f[2] * rs * gv[2], f[3] * rs * gv[3]);
;       v.z = pk2(f[4] * rs * gv[4], f[5] * rs * gv[5]); v.w = pk2(f[6] * rs * gv[6], f[7] * rs * gv[7]);
;     }
;     *(LAS u32x4*)(img + kl * KROW + dch * 16) = v;
.LBB0_550:
	s_or_saveexec_b64 s[6:7], s[6:7]
	v_mov_b32_e32 v62, v57
	v_mov_b32_e32 v63, v57
	s_xor_b64 exec, exec, s[6:7]
	v_mov_b64_e32 v[62:63], v[58:59]
	v_mov_b64_e32 v[60:61], v[56:57]
	s_or_b64 exec, exec, s[6:7]
	v_readlane_b32 s6, v253, 23
	v_readlane_b32 s7, v253, 24
	v_mov_b32_e32 v61, v57
	s_and_b64 vcc, exec, s[6:7]
	s_cbranch_vccz .LBB0_627
	v_lshlrev_b32_e32 v72, 16, v60
	v_and_b32_e32 v73, 0xffff0000, v60
	v_lshlrev_b32_e32 v68, 16, v61
	v_and_b32_e32 v69, 0xffff0000, v61
	v_pk_mul_f32 v[74:75], v[72:73], v[72:73]
	v_and_b32_e32 v57, 64, v225
	v_pk_mul_f32 v[70:71], v[68:69], v[68:69]
	v_add_f32_e32 v74, v74, v75
	v_xor_b32_e32 v56, 1, v225
	v_add_u32_e32 v77, 64, v57
	v_lshlrev_b32_e32 v58, 16, v62
	v_and_b32_e32 v59, 0xffff0000, v62
	v_add_f32_e32 v70, v70, v74
	v_cmp_lt_i32_e32 vcc, v56, v77
	v_pk_mul_f32 v[66:67], v[58:59], v[58:59]
	v_add_f32_e32 v70, v71, v70
	v_cndmask_b32_e32 v56, v225, v56, vcc
	v_lshlrev_b32_e32 v64, 16, v63
	v_and_b32_e32 v65, 0xffff0000, v63
	v_add_f32_e32 v66, v66, v70
	v_lshlrev_b32_e32 v78, 2, v56
	v_pk_mul_f32 v[56:57], v[64:65], v[64:65]
	v_add_f32_e32 v66, v67, v66
	v_add_f32_e32 v56, v56, v66
	v_add_f32_e32 v56, v57, v56
	s_mov_b32 s6, 0x800000
	s_nop 1
	v_add_f32_dpp v56, v56, v56 quad_perm:[1,0,3,2] row_mask:0xf bank_mask:0xf
	s_nop 1
	v_add_f32_dpp v56, v56, v56 quad_perm:[2,3,0,1] row_mask:0xf bank_mask:0xf
	s_nop 1
	v_add_f32_dpp v56, v56, v56 row_half_mirror row_mask:0xf bank_mask:0xf
	s_nop 1
	v_add_f32_dpp v56, v56, v56 row_mirror row_mask:0xf bank_mask:0xf
	v_fmamk_f32 v56, v56, 0x3c000000, v218
	v_mul_f32_e32 v57, 0x4b800000, v56
	v_cmp_gt_f32_e32 vcc, s6, v56
	s_nop 1
	v_cndmask_b32_e32 v56, v56, v57, vcc
	v_rsq_f32_e32 v56, v56
	s_nop 0
	v_mul_f32_e32 v57, 0x45800000, v56
	v_cndmask_b32_e32 v66, v56, v57, vcc
	v_pk_mul_f32 v[56:57], v[66:67], v[72:73] op_sel_hi:[0,1]
	v_pk_mul_f32 v[68:69], v[66:67], v[68:69] op_sel_hi:[0,1]
	v_pk_mul_f32 v[58:59], v[66:67], v[58:59] op_sel_hi:[0,1]
	v_pk_mul_f32 v[64:65], v[66:67], v[64:65] op_sel_hi:[0,1]
	v_pk_mul_f32 v[56:57], v[4:5], v[56:57]
	v_pk_mul_f32 v[68:69], v[6:7], v[68:69]
	v_pk_mul_f32 v[58:59], v[0:1], v[58:59]
	v_pk_mul_f32 v[64:65], v[2:3], v[64:65]
	v_cvt_pk_bf16_f32 v56, v56, v57
	v_cvt_pk_bf16_f32 v57, v68, v69
	v_cvt_pk_bf16_f32 v58, v58, v59
	v_cvt_pk_bf16_f32 v59, v64, v65
	s_cbranch_execnz .LBB0_555

; #define LAS __attribute__((address_space(3)))
; #define LAUNDER_V(x) asm volatile("" : "+v"(x))
; __device__ __forceinline__ unsigned pk2(float lo, float hi) { const f32x2_t f = {lo, hi}; const bf16x2_t b = __builtin_convertvector(f, bf16x2_t); return __builtin_bit_cast(unsigned, b); }
; __device__ __forceinline__ float lo16(unsigned v) { return __uint_as_float(v << 16); }
; __device__ __forceinline__ float hi16(unsigned v) { return __uint_as_float(v & 0xffff0000u); }
; __device__ __forceinline__ void stage_kv(const u16* src_base_  , int b, int L, int dil, int r, int m0, int M, LAS unsigned char* img, const float* gk, int ht) {
;     ...
;     if (!valid) { v.x = 0u; LAUNDER_V(v.x); v.y = v.x; v.z = v.x; v.w = v.x; }
;     if (gk) {
;       float f[8] = {lo16(v.x), hi16(v.x), lo16(v.y), hi16(v.y), lo16(v.z), hi16(v.z), lo16(v.w), hi16(v.w)};
;       float s = 0.f;
; #pragma unroll
;       for (int e = 0; e < 8; ++e) s += f[e] * f[e];
;       s += __shfl_xor(s, 1); s += __shfl_xor(s, 2); s += __shfl_xor(s, 4); s += __shfl_xor(s, 8);
;       const float rs = rsqrtf(s * (1.0f / 128.0f) + 1e-6f);
;       v.x = pk2(f[0] * rs * gv[0], f[1] * rs * gv[1]); v.y = pk2(f[2] * rs * gv[2], f[3] * rs * gv[3]);
;       v.z = pk2(f[4] * rs * gv[4], f[5] * rs * gv[5]); v.w = pk2(f[6] * rs * gv[6], f[7] * rs * gv[7]);
;     }
;     *(LAS u32x4*)(img + kl * KROW + dch * 16) = v;
.LBB0_557:
	s_or_saveexec_b64 s[8:9], s[8:9]
	v_mov_b32_e32 v58, v53
	v_mov_b32_e32 v59, v53
	s_xor_b64 exec, exec, s[8:9]
	v_mov_b64_e32 v[58:59], v[54:55]
	v_mov_b64_e32 v[56:57], v[52:53]
	s_or_b64 exec, exec, s[8:9]
	v_readlane_b32 s8, v253, 23
	v_readlane_b32 s9, v253, 24
	v_mov_b32_e32 v57, v53
	s_and_b64 vcc, exec, s[8:9]
	s_cbranch_vccz .LBB0_628
	v_lshlrev_b32_e32 v68, 16, v56
	v_and_b32_e32 v69, 0xffff0000, v56
	v_lshlrev_b32_e32 v64, 16, v57
	v_and_b32_e32 v65, 0xffff0000, v57
	v_pk_mul_f32 v[70:71], v[68:69], v[68:69]
	v_and_b32_e32 v53, 64, v225
	v_pk_mul_f32 v[66:67], v[64:65], v[64:65]
	v_add_f32_e32 v70, v70, v71
	v_xor_b32_e32 v52, 1, v225
	v_add_u32_e32 v72, 64, v53
	v_lshlrev_b32_e32 v54, 16, v58
	v_and_b32_e32 v55, 0xffff0000, v58
	v_add_f32_e32 v66, v66, v70
	v_cmp_lt_i32_e32 vcc, v52, v72
	v_pk_mul_f32 v[62:63], v[54:55], v[54:55]
	v_add_f32_e32 v66, v67, v66
	v_cndmask_b32_e32 v52, v225, v52, vcc
	v_lshlrev_b32_e32 v60, 16, v59
	v_and_b32_e32 v61, 0xffff0000, v59
	v_add_f32_e32 v62, v62, v66
	v_lshlrev_b32_e32 v73, 2, v52
	v_pk_mul_f32 v[52:53], v[60:61], v[60:61]
	v_add_f32_e32 v62, v63, v62
	v_add_f32_e32 v52, v52, v62
	v_add_f32_e32 v52, v53, v52
	s_mov_b32 s8, 0x800000
	s_nop 1
	v_add_f32_dpp v52, v52, v52 quad_perm:[1,0,3,2] row_mask:0xf bank_mask:0xf
	s_nop 1
	v_add_f32_dpp v52, v52, v52 quad_perm:[2,3,0,1] row_mask:0xf bank_mask:0xf
	s_nop 1
	v_add_f32_dpp v52, v52, v52 row_half_mirror row_mask:0xf bank_mask:0xf
	s_nop 1
	v_add_f32_dpp v52, v52, v52 row_mirror row_mask:0xf bank_mask:0xf
	v_fmamk_f32 v52, v52, 0x3c000000, v218
	v_mul_f32_e32 v53, 0x4b800000, v52
	v_cmp_gt_f32_e32 vcc, s8, v52
	s_nop 1
	v_cndmask_b32_e32 v52, v52, v53, vcc
	v_rsq_f32_e32 v52, v52
	s_nop 0
	v_mul_f32_e32 v53, 0x45800000, v52
	v_cndmask_b32_e32 v62, v52, v53, vcc
	v_pk_mul_f32 v[52:53], v[62:63], v[68:69] op_sel_hi:[0,1]
	v_pk_mul_f32 v[64:65], v[62:63], v[64:65] op_sel_hi:[0,1]
	v_pk_mul_f32 v[54:55], v[62:63], v[54:55] op_sel_hi:[0,1]
	v_pk_mul_f32 v[60:61], v[62:63], v[60:61] op_sel_hi:[0,1]
	v_pk_mul_f32 v[52:53], v[4:5], v[52:53]
	v_pk_mul_f32 v[64:65], v[6:7], v[64:65]
	v_pk_mul_f32 v[54:55], v[0:1], v[54:55]
	v_pk_mul_f32 v[60:61], v[2:3], v[60:61]
	v_cvt_pk_bf16_f32 v52, v52, v53
	v_cvt_pk_bf16_f32 v53, v64, v65
	v_cvt_pk_bf16_f32 v54, v54, v55
	v_cvt_pk_bf16_f32 v55, v60, v61
	s_cbranch_execnz .LBB0_562

; #define LAS __attribute__((address_space(3)))
; #define LAUNDER_V(x) asm volatile("" : "+v"(x))
; __device__ __forceinline__ unsigned pk2(float lo, float hi) { const f32x2_t f = {lo, hi}; const bf16x2_t b = __builtin_convertvector(f, bf16x2_t); return __builtin_bit_cast(unsigned, b); }
; __device__ __forceinline__ float lo16(unsigned v) { return __uint_as_float(v << 16); }
; __device__ __forceinline__ float hi16(unsigned v) { return __uint_as_float(v & 0xffff0000u); }
; __device__ __forceinline__ void stage_kv(const u16* src_base_  , int b, int L, int dil, int r, int m0, int M, LAS unsigned char* img, const float* gk, int ht) {
;     ...
;     if (!valid) { v.x = 0u; LAUNDER_V(v.x); v.y = v.x; v.z = v.x; v.w = v.x; }
;     if (gk) {
;       float f[8] = {lo16(v.x), hi16(v.x), lo16(v.y), hi16(v.y), lo16(v.z), hi16(v.z), lo16(v.w), hi16(v.w)};
;       float s = 0.f;
; #pragma unroll
;       for (int e = 0; e < 8; ++e) s += f[e] * f[e];
;       s += __shfl_xor(s, 1); s += __shfl_xor(s, 2); s += __shfl_xor(s, 4); s += __shfl_xor(s, 8);
;       const float rs = rsqrtf(s * (1.0f / 128.0f) + 1e-6f);
;       v.x = pk2(f[0] * rs * gv[0], f[1] * rs * gv[1]); v.y = pk2(f[2] * rs * gv[2], f[3] * rs * gv[3]);
;       v.z = pk2(f[4] * rs * gv[4], f[5] * rs * gv[5]); v.w = pk2(f[6] * rs * gv[6], f[7] * rs * gv[7]);
;     }
;     *(LAS u32x4*)(img + kl * KROW + dch * 16) = v;
.LBB0_564:
	s_or_saveexec_b64 s[10:11], s[10:11]
	v_mov_b32_e32 v54, v49
	v_mov_b32_e32 v55, v49
	s_xor_b64 exec, exec, s[10:11]
	v_mov_b64_e32 v[54:55], v[50:51]
	v_mov_b64_e32 v[52:53], v[48:49]
	s_or_b64 exec, exec, s[10:11]
	v_readlane_b32 s10, v253, 23
	v_readlane_b32 s11, v253, 24
	v_mov_b32_e32 v53, v49
	s_and_b64 vcc, exec, s[10:11]
	s_cbranch_vccz .LBB0_629
	v_lshlrev_b32_e32 v66, 16, v52
	v_and_b32_e32 v67, 0xffff0000, v52
	v_lshlrev_b32_e32 v62, 16, v53
	v_and_b32_e32 v63, 0xffff0000, v53
	v_pk_mul_f32 v[68:69], v[66:67], v[66:67]
	v_and_b32_e32 v49, 64, v225
	v_pk_mul_f32 v[64:65], v[62:63], v[62:63]
	v_add_f32_e32 v68, v68, v69
	v_xor_b32_e32 v48, 1, v225
	v_add_u32_e32 v57, 64, v49
	v_lshlrev_b32_e32 v50, 16, v54
	v_and_b32_e32 v51, 0xffff0000, v54
	v_add_f32_e32 v64, v64, v68
	v_cmp_lt_i32_e32 vcc, v48, v57
	v_pk_mul_f32 v[60:61], v[50:51], v[50:51]
	v_add_f32_e32 v64, v65, v64
	v_cndmask_b32_e32 v48, v225, v48, vcc
	v_lshlrev_b32_e32 v58, 16, v55
	v_and_b32_e32 v59, 0xffff0000, v55
	v_add_f32_e32 v60, v60, v64
	v_lshlrev_b32_e32 v70, 2, v48
	v_pk_mul_f32 v[48:49], v[58:59], v[58:59]
	v_add_f32_e32 v60, v61, v60
	v_add_f32_e32 v48, v48, v60
	v_add_f32_e32 v48, v49, v48
	s_mov_b32 s10, 0x800000
	s_nop 1
	v_add_f32_dpp v48, v48, v48 quad_perm:[1,0,3,2] row_mask:0xf bank_mask:0xf
	s_nop 1
	v_add_f32_dpp v48, v48, v48 quad_perm:[2,3,0,1] row_mask:0xf bank_mask:0xf
	s_nop 1
	v_add_f32_dpp v48, v48, v48 row_half_mirror row_mask:0xf bank_mask:0xf
	s_nop 1
	v_add_f32_dpp v48, v48, v48 row_mirror row_mask:0xf bank_mask:0xf
	v_fmamk_f32 v48, v48, 0x3c000000, v218
	v_mul_f32_e32 v49, 0x4b800000, v48
	v_cmp_gt_f32_e32 vcc, s10, v48
	s_nop 1
	v_cndmask_b32_e32 v48, v48, v49, vcc
	v_rsq_f32_e32 v48, v48
	s_nop 0
	v_mul_f32_e32 v49, 0x45800000, v48
	v_cndmask_b32_e32 v60, v48, v49, vcc
	v_pk_mul_f32 v[48:49], v[60:61], v[66:67] op_sel_hi:[0,1]
	v_pk_mul_f32 v[62:63], v[60:61], v[62:63] op_sel_hi:[0,1]
	v_pk_mul_f32 v[50:51], v[60:61], v[50:51] op_sel_hi:[0,1]
	v_pk_mul_f32 v[58:59], v[60:61], v[58:59] op_sel_hi:[0,1]
	v_pk_mul_f32 v[48:49], v[4:5], v[48:49]
	v_pk_mul_f32 v[62:63], v[6:7], v[62:63]
	v_pk_mul_f32 v[50:51], v[0:1], v[50:51]
	v_pk_mul_f32 v[58:59], v[2:3], v[58:59]
	v_cvt_pk_bf16_f32 v48, v48, v49
	v_cvt_pk_bf16_f32 v49, v62, v63
	v_cvt_pk_bf16_f32 v50, v50, v51
	v_cvt_pk_bf16_f32 v51, v58, v59
	s_cbranch_execnz .LBB0_569

; #define LAS __attribute__((address_space(3)))
; #define LAUNDER_V(x) asm volatile("" : "+v"(x))
; __device__ __forceinline__ unsigned pk2(float lo, float hi) { const f32x2_t f = {lo, hi}; const bf16x2_t b = __builtin_convertvector(f, bf16x2_t); return __builtin_bit_cast(unsigned, b); }
; __device__ __forceinline__ float lo16(unsigned v) { return __uint_as_float(v << 16); }
; __device__ __forceinline__ float hi16(unsigned v) { return __uint_as_float(v & 0xffff0000u); }
; __device__ __forceinline__ void stage_kv(const u16* src_base_  , int b, int L, int dil, int r, int m0, int M, LAS unsigned char* img, const float* gk, int ht) {
;     ...
;     if (!valid) { v.x = 0u; LAUNDER_V(v.x); v.y = v.x; v.z = v.x; v.w = v.x; }
;     if (gk) {
;       float f[8] = {lo16(v.x), hi16(v.x), lo16(v.y), hi16(v.y), lo16(v.z), hi16(v.z), lo16(v.w), hi16(v.w)};
;       float s = 0.f;
; #pragma unroll
;       for (int e = 0; e < 8; ++e) s += f[e] * f[e];
;       s += __shfl_xor(s, 1); s += __shfl_xor(s, 2); s += __shfl_xor(s, 4); s += __shfl_xor(s, 8);
;       const float rs = rsqrtf(s * (1.0f / 128.0f) + 1e-6f);
;       v.x = pk2(f[0] * rs * gv[0], f[1] * rs * gv[1]); v.y = pk2(f[2] * rs * gv[2], f[3] * rs * gv[3]);
;       v.z = pk2(f[4] * rs * gv[4], f[5] * rs * gv[5]); v.w = pk2(f[6] * rs * gv[6], f[7] * rs * gv[7]);
;     }
;     *(LAS u32x4*)(img + kl * KROW + dch * 16) = v;
.LBB0_571:
	s_or_saveexec_b64 s[12:13], s[12:13]
	v_mov_b32_e32 v50, v45
	v_mov_b32_e32 v51, v45
	s_xor_b64 exec, exec, s[12:13]
	v_mov_b64_e32 v[50:51], v[46:47]
	v_mov_b64_e32 v[48:49], v[44:45]
	s_or_b64 exec, exec, s[12:13]
	v_readlane_b32 s12, v253, 23
	v_readlane_b32 s13, v253, 24
	v_mov_b32_e32 v49, v45
	s_and_b64 vcc, exec, s[12:13]
	s_cbranch_vccz .LBB0_630
	v_lshlrev_b32_e32 v62, 16, v48
	v_and_b32_e32 v63, 0xffff0000, v48
	v_lshlrev_b32_e32 v58, 16, v49
	v_and_b32_e32 v59, 0xffff0000, v49
	v_pk_mul_f32 v[64:65], v[62:63], v[62:63]
	v_and_b32_e32 v45, 64, v225
	v_pk_mul_f32 v[60:61], v[58:59], v[58:59]
	v_add_f32_e32 v64, v64, v65
	v_xor_b32_e32 v44, 1, v225
	v_add_u32_e32 v57, 64, v45
	v_lshlrev_b32_e32 v46, 16, v50
	v_and_b32_e32 v47, 0xffff0000, v50
	v_add_f32_e32 v60, v60, v64
	v_cmp_lt_i32_e32 vcc, v44, v57
	v_pk_mul_f32 v[54:55], v[46:47], v[46:47]
	v_add_f32_e32 v60, v61, v60
	v_cndmask_b32_e32 v44, v225, v44, vcc
	v_lshlrev_b32_e32 v52, 16, v51
	v_and_b32_e32 v53, 0xffff0000, v51
	v_add_f32_e32 v54, v54, v60
	v_lshlrev_b32_e32 v66, 2, v44
	v_pk_mul_f32 v[44:45], v[52:53], v[52:53]
	v_add_f32_e32 v54, v55, v54
	v_add_f32_e32 v44, v44, v54
	v_add_f32_e32 v44, v45, v44
	s_mov_b32 s12, 0x800000
	s_nop 1
	v_add_f32_dpp v44, v44, v44 quad_perm:[1,0,3,2] row_mask:0xf bank_mask:0xf
	s_nop 1
	v_add_f32_dpp v44, v44, v44 quad_perm:[2,3,0,1] row_mask:0xf bank_mask:0xf
	s_nop 1
	v_add_f32_dpp v44, v44, v44 row_half_mirror row_mask:0xf bank_mask:0xf
	s_nop 1
	v_add_f32_dpp v44, v44, v44 row_mirror row_mask:0xf bank_mask:0xf
	v_fmamk_f32 v44, v44, 0x3c000000, v218
	v_mul_f32_e32 v45, 0x4b800000, v44
	v_cmp_gt_f32_e32 vcc, s12, v44
	s_nop 1
	v_cndmask_b32_e32 v44, v44, v45, vcc
	v_rsq_f32_e32 v44, v44
	s_nop 0
	v_mul_f32_e32 v45, 0x45800000, v44
	v_cndmask_b32_e32 v54, v44, v45, vcc
	v_pk_mul_f32 v[44:45], v[54:55], v[62:63] op_sel_hi:[0,1]
	v_pk_mul_f32 v[58:59], v[54:55], v[58:59] op_sel_hi:[0,1]
	v_pk_mul_f32 v[46:47], v[54:55], v[46:47] op_sel_hi:[0,1]
	v_pk_mul_f32 v[52:53], v[54:55], v[52:53] op_sel_hi:[0,1]
	v_pk_mul_f32 v[44:45], v[4:5], v[44:45]
	v_pk_mul_f32 v[58:59], v[6:7], v[58:59]
	v_pk_mul_f32 v[46:47], v[0:1], v[46:47]
	v_pk_mul_f32 v[52:53], v[2:3], v[52:53]
	v_cvt_pk_bf16_f32 v44, v44, v45
	v_cvt_pk_bf16_f32 v45, v58, v59
	v_cvt_pk_bf16_f32 v46, v46, v47
	v_cvt_pk_bf16_f32 v47, v52, v53
	s_cbranch_execnz .LBB0_576

; #define LAS __attribute__((address_space(3)))
; #define LAUNDER_V(x) asm volatile("" : "+v"(x))
; __device__ __forceinline__ unsigned pk2(float lo, float hi) { const f32x2_t f = {lo, hi}; const bf16x2_t b = __builtin_convertvector(f, bf16x2_t); return __builtin_bit_cast(unsigned, b); }
; __device__ __forceinline__ float lo16(unsigned v) { return __uint_as_float(v << 16); }
; __device__ __forceinline__ float hi16(unsigned v) { return __uint_as_float(v & 0xffff0000u); }
; __device__ __forceinline__ void stage_kv(const u16* src_base_  , int b, int L, int dil, int r, int m0, int M, LAS unsigned char* img, const float* gk, int ht) {
;     ...
;     if (!valid) { v.x = 0u; LAUNDER_V(v.x); v.y = v.x; v.z = v.x; v.w = v.x; }
;     if (gk) {
;       float f[8] = {lo16(v.x), hi16(v.x), lo16(v.y), hi16(v.y), lo16(v.z), hi16(v.z), lo16(v.w), hi16(v.w)};
;       float s = 0.f;
; #pragma unroll
;       for (int e = 0; e < 8; ++e) s += f[e] * f[e];
;       s += __shfl_xor(s, 1); s += __shfl_xor(s, 2); s += __shfl_xor(s, 4); s += __shfl_xor(s, 8);
;       const float rs = rsqrtf(s * (1.0f / 128.0f) + 1e-6f);
;       v.x = pk2(f[0] * rs * gv[0], f[1] * rs * gv[1]); v.y = pk2(f[2] * rs * gv[2], f[3] * rs * gv[3]);
;       v.z = pk2(f[4] * rs * gv[4], f[5] * rs * gv[5]); v.w = pk2(f[6] * rs * gv[6], f[7] * rs * gv[7]);
;     }
;     *(LAS u32x4*)(img + kl * KROW + dch * 16) = v;
.LBB0_578:
	s_or_saveexec_b64 s[14:15], s[14:15]
	v_mov_b32_e32 v46, v41
	v_mov_b32_e32 v47, v41
	s_xor_b64 exec, exec, s[14:15]
	v_mov_b64_e32 v[46:47], v[42:43]
	v_mov_b64_e32 v[44:45], v[40:41]
	s_or_b64 exec, exec, s[14:15]
	v_readlane_b32 s14, v253, 23
	v_readlane_b32 s15, v253, 24
	v_mov_b32_e32 v45, v41
	s_and_b64 vcc, exec, s[14:15]
	s_cbranch_vccz .LBB0_631
	v_lshlrev_b32_e32 v58, 16, v44
	v_and_b32_e32 v59, 0xffff0000, v44
	v_lshlrev_b32_e32 v52, 16, v45
	v_and_b32_e32 v53, 0xffff0000, v45
	v_pk_mul_f32 v[60:61], v[58:59], v[58:59]
	v_and_b32_e32 v41, 64, v225
	v_pk_mul_f32 v[54:55], v[52:53], v[52:53]
	v_add_f32_e32 v60, v60, v61
	v_xor_b32_e32 v40, 1, v225
	v_add_u32_e32 v57, 64, v41
	v_lshlrev_b32_e32 v42, 16, v46
	v_and_b32_e32 v43, 0xffff0000, v46
	v_add_f32_e32 v54, v54, v60
	v_cmp_lt_i32_e32 vcc, v40, v57
	v_pk_mul_f32 v[50:51], v[42:43], v[42:43]
	v_add_f32_e32 v54, v55, v54
	v_cndmask_b32_e32 v40, v225, v40, vcc
	v_lshlrev_b32_e32 v48, 16, v47
	v_and_b32_e32 v49, 0xffff0000, v47
	v_add_f32_e32 v50, v50, v54
	v_lshlrev_b32_e32 v62, 2, v40
	v_pk_mul_f32 v[40:41], v[48:49], v[48:49]
	v_add_f32_e32 v50, v51, v50
	v_add_f32_e32 v40, v40, v50
	v_add_f32_e32 v40, v41, v40
	s_mov_b32 s14, 0x800000
	s_nop 1
	v_add_f32_dpp v40, v40, v40 quad_perm:[1,0,3,2] row_mask:0xf bank_mask:0xf
	s_nop 1
	v_add_f32_dpp v40, v40, v40 quad_perm:[2,3,0,1] row_mask:0xf bank_mask:0xf
	s_nop 1
	v_add_f32_dpp v40, v40, v40 row_half_mirror row_mask:0xf bank_mask:0xf
	s_nop 1
	v_add_f32_dpp v40, v40, v40 row_mirror row_mask:0xf bank_mask:0xf
	v_fmamk_f32 v40, v40, 0x3c000000, v218
	v_mul_f32_e32 v41, 0x4b800000, v40
	v_cmp_gt_f32_e32 vcc, s14, v40
	s_nop 1
	v_cndmask_b32_e32 v40, v40, v41, vcc
	v_rsq_f32_e32 v40, v40
	s_nop 0
	v_mul_f32_e32 v41, 0x45800000, v40
	v_cndmask_b32_e32 v50, v40, v41, vcc
	v_pk_mul_f32 v[40:41], v[50:51], v[58:59] op_sel_hi:[0,1]
	v_pk_mul_f32 v[52:53], v[50:51], v[52:53] op_sel_hi:[0,1]
	v_pk_mul_f32 v[42:43], v[50:51], v[42:43] op_sel_hi:[0,1]
	v_pk_mul_f32 v[48:49], v[50:51], v[48:49] op_sel_hi:[0,1]
	v_pk_mul_f32 v[40:41], v[4:5], v[40:41]
	v_pk_mul_f32 v[52:53], v[6:7], v[52:53]
	v_pk_mul_f32 v[42:43], v[0:1], v[42:43]
	v_pk_mul_f32 v[48:49], v[2:3], v[48:49]
	v_cvt_pk_bf16_f32 v40, v40, v41
	v_cvt_pk_bf16_f32 v41, v52, v53
	v_cvt_pk_bf16_f32 v42, v42, v43
	v_cvt_pk_bf16_f32 v43, v48, v49
	s_cbranch_execnz .LBB0_583

; #define LAS __attribute__((address_space(3)))
; #define LAUNDER_V(x) asm volatile("" : "+v"(x))
; __device__ __forceinline__ unsigned pk2(float lo, float hi) { const f32x2_t f = {lo, hi}; const bf16x2_t b = __builtin_convertvector(f, bf16x2_t); return __builtin_bit_cast(unsigned, b); }
; __device__ __forceinline__ float lo16(unsigned v) { return __uint_as_float(v << 16); }
; __device__ __forceinline__ float hi16(unsigned v) { return __uint_as_float(v & 0xffff0000u); }
; __device__ __forceinline__ void stage_kv(const u16* src_base_  , int b, int L, int dil, int r, int m0, int M, LAS unsigned char* img, const float* gk, int ht) {
;     ...
;     if (!valid) { v.x = 0u; LAUNDER_V(v.x); v.y = v.x; v.z = v.x; v.w = v.x; }
;     if (gk) {
;       float f[8] = {lo16(v.x), hi16(v.x), lo16(v.y), hi16(v.y), lo16(v.z), hi16(v.z), lo16(v.w), hi16(v.w)};
;       float s = 0.f;
; #pragma unroll
;       for (int e = 0; e < 8; ++e) s += f[e] * f[e];
;       s += __shfl_xor(s, 1); s += __shfl_xor(s, 2); s += __shfl_xor(s, 4); s += __shfl_xor(s, 8);
;       const float rs = rsqrtf(s * (1.0f / 128.0f) + 1e-6f);
;       v.x = pk2(f[0] * rs * gv[0], f[1] * rs * gv[1]); v.y = pk2(f[2] * rs * gv[2], f[3] * rs * gv[3]);
;       v.z = pk2(f[4] * rs * gv[4], f[5] * rs * gv[5]); v.w = pk2(f[6] * rs * gv[6], f[7] * rs * gv[7]);
;     }
;     *(LAS u32x4*)(img + kl * KROW + dch * 16) = v;
.LBB0_585:
	s_or_saveexec_b64 s[16:17], s[16:17]
	v_mov_b32_e32 v42, v37
	v_mov_b32_e32 v43, v37
	s_xor_b64 exec, exec, s[16:17]
	v_mov_b64_e32 v[42:43], v[38:39]
	v_mov_b64_e32 v[40:41], v[36:37]
	s_or_b64 exec, exec, s[16:17]
	v_readlane_b32 s16, v253, 23
	v_readlane_b32 s17, v253, 24
	v_mov_b32_e32 v41, v37
	s_and_b64 vcc, exec, s[16:17]
	s_cbranch_vccz .LBB0_632
	v_lshlrev_b32_e32 v52, 16, v40
	v_and_b32_e32 v53, 0xffff0000, v40
	v_lshlrev_b32_e32 v48, 16, v41
	v_and_b32_e32 v49, 0xffff0000, v41
	v_pk_mul_f32 v[54:55], v[52:53], v[52:53]
	v_and_b32_e32 v37, 64, v225
	v_pk_mul_f32 v[50:51], v[48:49], v[48:49]
	v_add_f32_e32 v54, v54, v55
	v_xor_b32_e32 v36, 1, v225
	v_add_u32_e32 v57, 64, v37
	v_lshlrev_b32_e32 v38, 16, v42
	v_and_b32_e32 v39, 0xffff0000, v42
	v_add_f32_e32 v50, v50, v54
	v_cmp_lt_i32_e32 vcc, v36, v57
	v_pk_mul_f32 v[46:47], v[38:39], v[38:39]
	v_add_f32_e32 v50, v51, v50
	v_cndmask_b32_e32 v36, v225, v36, vcc
	v_lshlrev_b32_e32 v44, 16, v43
	v_and_b32_e32 v45, 0xffff0000, v43
	v_add_f32_e32 v46, v46, v50
	v_lshlrev_b32_e32 v58, 2, v36
	v_pk_mul_f32 v[36:37], v[44:45], v[44:45]
	v_add_f32_e32 v46, v47, v46
	v_add_f32_e32 v36, v36, v46
	v_add_f32_e32 v36, v37, v36
	s_mov_b32 s16, 0x800000
	s_nop 1
	v_add_f32_dpp v36, v36, v36 quad_perm:[1,0,3,2] row_mask:0xf bank_mask:0xf
	s_nop 1
	v_add_f32_dpp v36, v36, v36 quad_perm:[2,3,0,1] row_mask:0xf bank_mask:0xf
	s_nop 1
	v_add_f32_dpp v36, v36, v36 row_half_mirror row_mask:0xf bank_mask:0xf
	s_nop 1
	v_add_f32_dpp v36, v36, v36 row_mirror row_mask:0xf bank_mask:0xf
	v_fmamk_f32 v36, v36, 0x3c000000, v218
	v_mul_f32_e32 v37, 0x4b800000, v36
	v_cmp_gt_f32_e32 vcc, s16, v36
	s_nop 1
	v_cndmask_b32_e32 v36, v36, v37, vcc
	v_rsq_f32_e32 v36, v36
	s_nop 0
	v_mul_f32_e32 v37, 0x45800000, v36
	v_cndmask_b32_e32 v46, v36, v37, vcc
	v_pk_mul_f32 v[36:37], v[46:47], v[52:53] op_sel_hi:[0,1]
	v_pk_mul_f32 v[48:49], v[46:47], v[48:49] op_sel_hi:[0,1]
	v_pk_mul_f32 v[38:39], v[46:47], v[38:39] op_sel_hi:[0,1]
	v_pk_mul_f32 v[44:45], v[46:47], v[44:45] op_sel_hi:[0,1]
	v_pk_mul_f32 v[36:37], v[4:5], v[36:37]
	v_pk_mul_f32 v[48:49], v[6:7], v[48:49]
	v_pk_mul_f32 v[38:39], v[0:1], v[38:39]
	v_pk_mul_f32 v[44:45], v[2:3], v[44:45]
	v_cvt_pk_bf16_f32 v36, v36, v37
	v_cvt_pk_bf16_f32 v37, v48, v49
	v_cvt_pk_bf16_f32 v38, v38, v39
	v_cvt_pk_bf16_f32 v39, v44, v45
	s_cbranch_execnz .LBB0_590

; #define LAS __attribute__((address_space(3)))
; #define LAUNDER_V(x) asm volatile("" : "+v"(x))
; __device__ __forceinline__ unsigned pk2(float lo, float hi) { const f32x2_t f = {lo, hi}; const bf16x2_t b = __builtin_convertvector(f, bf16x2_t); return __builtin_bit_cast(unsigned, b); }
; __device__ __forceinline__ float lo16(unsigned v) { return __uint_as_float(v << 16); }
; __device__ __forceinline__ float hi16(unsigned v) { return __uint_as_float(v & 0xffff0000u); }
; __device__ __forceinline__ void stage_kv(const u16* src_base_  , int b, int L, int dil, int r, int m0, int M, LAS unsigned char* img, const float* gk, int ht) {
;     ...
;     if (!valid) { v.x = 0u; LAUNDER_V(v.x); v.y = v.x; v.z = v.x; v.w = v.x; }
;     if (gk) {
;       float f[8] = {lo16(v.x), hi16(v.x), lo16(v.y), hi16(v.y), lo16(v.z), hi16(v.z), lo16(v.w), hi16(v.w)};
;       float s = 0.f;
; #pragma unroll
;       for (int e = 0; e < 8; ++e) s += f[e] * f[e];
;       s += __shfl_xor(s, 1); s += __shfl_xor(s, 2); s += __shfl_xor(s, 4); s += __shfl_xor(s, 8);
;       const float rs = rsqrtf(s * (1.0f / 128.0f) + 1e-6f);
;       v.x = pk2(f[0] * rs * gv[0], f[1] * rs * gv[1]); v.y = pk2(f[2] * rs * gv[2], f[3] * rs * gv[3]);
;       v.z = pk2(f[4] * rs * gv[4], f[5] * rs * gv[5]); v.w = pk2(f[6] * rs * gv[6], f[7] * rs * gv[7]);
;     }
;     *(LAS u32x4*)(img + kl * KROW + dch * 16) = v;
.LBB0_592:
	s_or_saveexec_b64 s[18:19], s[18:19]
	v_mov_b32_e32 v38, v33
	v_mov_b32_e32 v39, v33
	s_xor_b64 exec, exec, s[18:19]
	v_mov_b64_e32 v[38:39], v[34:35]
	v_mov_b64_e32 v[36:37], v[32:33]
	s_or_b64 exec, exec, s[18:19]
	v_readlane_b32 s18, v253, 23
	v_readlane_b32 s19, v253, 24
	v_mov_b32_e32 v37, v33
	s_and_b64 vcc, exec, s[18:19]
	s_cbranch_vccz .LBB0_633
	v_lshlrev_b32_e32 v48, 16, v36
	v_and_b32_e32 v49, 0xffff0000, v36
	v_lshlrev_b32_e32 v44, 16, v37
	v_and_b32_e32 v45, 0xffff0000, v37
	v_pk_mul_f32 v[50:51], v[48:49], v[48:49]
	v_and_b32_e32 v33, 64, v225
	v_pk_mul_f32 v[46:47], v[44:45], v[44:45]
	v_add_f32_e32 v50, v50, v51
	v_xor_b32_e32 v32, 1, v225
	v_add_u32_e32 v52, 64, v33
	v_lshlrev_b32_e32 v34, 16, v38
	v_and_b32_e32 v35, 0xffff0000, v38
	v_add_f32_e32 v46, v46, v50
	v_cmp_lt_i32_e32 vcc, v32, v52
	v_pk_mul_f32 v[42:43], v[34:35], v[34:35]
	v_add_f32_e32 v46, v47, v46
	v_cndmask_b32_e32 v32, v225, v32, vcc
	v_lshlrev_b32_e32 v40, 16, v39
	v_and_b32_e32 v41, 0xffff0000, v39
	v_add_f32_e32 v42, v42, v46
	v_lshlrev_b32_e32 v53, 2, v32
	v_pk_mul_f32 v[32:33], v[40:41], v[40:41]
	v_add_f32_e32 v42, v43, v42
	v_add_f32_e32 v32, v32, v42
	v_add_f32_e32 v32, v33, v32
	s_mov_b32 s18, 0x800000
	s_nop 1
	v_add_f32_dpp v32, v32, v32 quad_perm:[1,0,3,2] row_mask:0xf bank_mask:0xf
	s_nop 1
	v_add_f32_dpp v32, v32, v32 quad_perm:[2,3,0,1] row_mask:0xf bank_mask:0xf
	s_nop 1
	v_add_f32_dpp v32, v32, v32 row_half_mirror row_mask:0xf bank_mask:0xf
	s_nop 1
	v_add_f32_dpp v32, v32, v32 row_mirror row_mask:0xf bank_mask:0xf
	v_fmamk_f32 v32, v32, 0x3c000000, v218
	v_mul_f32_e32 v33, 0x4b800000, v32
	v_cmp_gt_f32_e32 vcc, s18, v32
	s_nop 1
	v_cndmask_b32_e32 v32, v32, v33, vcc
	v_rsq_f32_e32 v32, v32
	s_nop 0
	v_mul_f32_e32 v33, 0x45800000, v32
	v_cndmask_b32_e32 v42, v32, v33, vcc
	v_pk_mul_f32 v[32:33], v[42:43], v[48:49] op_sel_hi:[0,1]
	v_pk_mul_f32 v[44:45], v[42:43], v[44:45] op_sel_hi:[0,1]
	v_pk_mul_f32 v[34:35], v[42:43], v[34:35] op_sel_hi:[0,1]
	v_pk_mul_f32 v[40:41], v[42:43], v[40:41] op_sel_hi:[0,1]
	v_pk_mul_f32 v[32:33], v[4:5], v[32:33]
	v_pk_mul_f32 v[44:45], v[6:7], v[44:45]
	v_pk_mul_f32 v[34:35], v[0:1], v[34:35]
	v_pk_mul_f32 v[40:41], v[2:3], v[40:41]
	v_cvt_pk_bf16_f32 v32, v32, v33
	v_cvt_pk_bf16_f32 v33, v44, v45
	v_cvt_pk_bf16_f32 v34, v34, v35
	v_cvt_pk_bf16_f32 v35, v40, v41
	s_cbranch_execnz .LBB0_597

; #define LAS __attribute__((address_space(3)))
; #define LAUNDER_V(x) asm volatile("" : "+v"(x))
; __device__ __forceinline__ unsigned pk2(float lo, float hi) { const f32x2_t f = {lo, hi}; const bf16x2_t b = __builtin_convertvector(f, bf16x2_t); return __builtin_bit_cast(unsigned, b); }
; __device__ __forceinline__ float lo16(unsigned v) { return __uint_as_float(v << 16); }
; __device__ __forceinline__ float hi16(unsigned v) { return __uint_as_float(v & 0xffff0000u); }
; __device__ __forceinline__ void stage_kv(const u16* src_base_  , int b, int L, int dil, int r, int m0, int M, LAS unsigned char* img, const float* gk, int ht) {
;     ...
;     if (!valid) { v.x = 0u; LAUNDER_V(v.x); v.y = v.x; v.z = v.x; v.w = v.x; }
;     if (gk) {
;       float f[8] = {lo16(v.x), hi16(v.x), lo16(v.y), hi16(v.y), lo16(v.z), hi16(v.z), lo16(v.w), hi16(v.w)};
;       float s = 0.f;
; #pragma unroll
;       for (int e = 0; e < 8; ++e) s += f[e] * f[e];
;       s += __shfl_xor(s, 1); s += __shfl_xor(s, 2); s += __shfl_xor(s, 4); s += __shfl_xor(s, 8);
;       const float rs = rsqrtf(s * (1.0f / 128.0f) + 1e-6f);
;       v.x = pk2(f[0] * rs * gv[0], f[1] * rs * gv[1]); v.y = pk2(f[2] * rs * gv[2], f[3] * rs * gv[3]);
;       v.z = pk2(f[4] * rs * gv[4], f[5] * rs * gv[5]); v.w = pk2(f[6] * rs * gv[6], f[7] * rs * gv[7]);
;     }
;     *(LAS u32x4*)(img + kl * KROW + dch * 16) = v;
.LBB0_599:
	s_or_saveexec_b64 s[20:21], s[20:21]
	v_mov_b32_e32 v34, v29
	v_mov_b32_e32 v35, v29
	s_xor_b64 exec, exec, s[20:21]
	v_mov_b64_e32 v[34:35], v[30:31]
	v_mov_b64_e32 v[32:33], v[28:29]
	s_or_b64 exec, exec, s[20:21]
	v_readlane_b32 s20, v253, 23
	v_readlane_b32 s21, v253, 24
	v_mov_b32_e32 v33, v29
	s_and_b64 vcc, exec, s[20:21]
	s_cbranch_vccz .LBB0_634
	v_lshlrev_b32_e32 v44, 16, v32
	v_and_b32_e32 v45, 0xffff0000, v32
	v_lshlrev_b32_e32 v40, 16, v33
	v_and_b32_e32 v41, 0xffff0000, v33
	v_pk_mul_f32 v[46:47], v[44:45], v[44:45]
	v_and_b32_e32 v29, 64, v225
	v_pk_mul_f32 v[42:43], v[40:41], v[40:41]
	v_add_f32_e32 v46, v46, v47
	v_xor_b32_e32 v28, 1, v225
	v_add_u32_e32 v48, 64, v29
	v_lshlrev_b32_e32 v30, 16, v34
	v_and_b32_e32 v31, 0xffff0000, v34
	v_add_f32_e32 v42, v42, v46
	v_cmp_lt_i32_e32 vcc, v28, v48
	v_pk_mul_f32 v[38:39], v[30:31], v[30:31]
	v_add_f32_e32 v42, v43, v42
	v_cndmask_b32_e32 v28, v225, v28, vcc
	v_lshlrev_b32_e32 v36, 16, v35
	v_and_b32_e32 v37, 0xffff0000, v35
	v_add_f32_e32 v38, v38, v42
	v_lshlrev_b32_e32 v49, 2, v28
	v_pk_mul_f32 v[28:29], v[36:37], v[36:37]
	v_add_f32_e32 v38, v39, v38
	v_add_f32_e32 v28, v28, v38
	v_add_f32_e32 v28, v29, v28
	s_mov_b32 s20, 0x800000
	s_nop 1
	v_add_f32_dpp v28, v28, v28 quad_perm:[1,0,3,2] row_mask:0xf bank_mask:0xf
	s_nop 1
	v_add_f32_dpp v28, v28, v28 quad_perm:[2,3,0,1] row_mask:0xf bank_mask:0xf
	s_nop 1
	v_add_f32_dpp v28, v28, v28 row_half_mirror row_mask:0xf bank_mask:0xf
	s_nop 1
	v_add_f32_dpp v28, v28, v28 row_mirror row_mask:0xf bank_mask:0xf
	v_fmamk_f32 v28, v28, 0x3c000000, v218
	v_mul_f32_e32 v29, 0x4b800000, v28
	v_cmp_gt_f32_e32 vcc, s20, v28
	s_nop 1
	v_cndmask_b32_e32 v28, v28, v29, vcc
	v_rsq_f32_e32 v28, v28
	s_nop 0
	v_mul_f32_e32 v29, 0x45800000, v28
	v_cndmask_b32_e32 v38, v28, v29, vcc
	v_pk_mul_f32 v[28:29], v[38:39], v[44:45] op_sel_hi:[0,1]
	v_pk_mul_f32 v[40:41], v[38:39], v[40:41] op_sel_hi:[0,1]
	v_pk_mul_f32 v[30:31], v[38:39], v[30:31] op_sel_hi:[0,1]
	v_pk_mul_f32 v[36:37], v[38:39], v[36:37] op_sel_hi:[0,1]
	v_pk_mul_f32 v[28:29], v[4:5], v[28:29]
	v_pk_mul_f32 v[40:41], v[6:7], v[40:41]
	v_pk_mul_f32 v[30:31], v[0:1], v[30:31]
	v_pk_mul_f32 v[36:37], v[2:3], v[36:37]
	v_cvt_pk_bf16_f32 v28, v28, v29
	v_cvt_pk_bf16_f32 v29, v40, v41
	v_cvt_pk_bf16_f32 v30, v30, v31
	v_cvt_pk_bf16_f32 v31, v36, v37
	s_cbranch_execnz .LBB0_604

; #define LAS __attribute__((address_space(3)))
; #define LAUNDER_V(x) asm volatile("" : "+v"(x))
; __device__ __forceinline__ unsigned pk2(float lo, float hi) { const f32x2_t f = {lo, hi}; const bf16x2_t b = __builtin_convertvector(f, bf16x2_t); return __builtin_bit_cast(unsigned, b); }
; __device__ __forceinline__ float lo16(unsigned v) { return __uint_as_float(v << 16); }
; __device__ __forceinline__ float hi16(unsigned v) { return __uint_as_float(v & 0xffff0000u); }
; __device__ __forceinline__ void stage_kv(const u16* src_base_  , int b, int L, int dil, int r, int m0, int M, LAS unsigned char* img, const float* gk, int ht) {
;     ...
;     if (!valid) { v.x = 0u; LAUNDER_V(v.x); v.y = v.x; v.z = v.x; v.w = v.x; }
;     if (gk) {
;       float f[8] = {lo16(v.x), hi16(v.x), lo16(v.y), hi16(v.y), lo16(v.z), hi16(v.z), lo16(v.w), hi16(v.w)};
;       float s = 0.f;
; #pragma unroll
;       for (int e = 0; e < 8; ++e) s += f[e] * f[e];
;       s += __shfl_xor(s, 1); s += __shfl_xor(s, 2); s += __shfl_xor(s, 4); s += __shfl_xor(s, 8);
;       const float rs = rsqrtf(s * (1.0f / 128.0f) + 1e-6f);
;       v.x = pk2(f[0] * rs * gv[0], f[1] * rs * gv[1]); v.y = pk2(f[2] * rs * gv[2], f[3] * rs * gv[3]);
;       v.z = pk2(f[4] * rs * gv[4], f[5] * rs * gv[5]); v.w = pk2(f[6] * rs * gv[6], f[7] * rs * gv[7]);
;     }
;     *(LAS u32x4*)(img + kl * KROW + dch * 16) = v;
.LBB0_606:
	s_or_saveexec_b64 s[22:23], s[22:23]
	v_mov_b32_e32 v30, v25
	v_mov_b32_e32 v31, v25
	s_xor_b64 exec, exec, s[22:23]
	v_mov_b64_e32 v[30:31], v[26:27]
	v_mov_b64_e32 v[28:29], v[24:25]
	s_or_b64 exec, exec, s[22:23]
	v_readlane_b32 s22, v253, 23
	v_readlane_b32 s23, v253, 24
	v_mov_b32_e32 v29, v25
	s_and_b64 vcc, exec, s[22:23]
	s_cbranch_vccz .LBB0_635
	v_lshlrev_b32_e32 v40, 16, v28
	v_and_b32_e32 v41, 0xffff0000, v28
	v_lshlrev_b32_e32 v36, 16, v29
	v_and_b32_e32 v37, 0xffff0000, v29
	v_pk_mul_f32 v[42:43], v[40:41], v[40:41]
	v_and_b32_e32 v25, 64, v225
	v_pk_mul_f32 v[38:39], v[36:37], v[36:37]
	v_add_f32_e32 v42, v42, v43
	v_xor_b32_e32 v24, 1, v225
	v_add_u32_e32 v44, 64, v25
	v_lshlrev_b32_e32 v26, 16, v30
	v_and_b32_e32 v27, 0xffff0000, v30
	v_add_f32_e32 v38, v38, v42
	v_cmp_lt_i32_e32 vcc, v24, v44
	v_pk_mul_f32 v[34:35], v[26:27], v[26:27]
	v_add_f32_e32 v38, v39, v38
	v_cndmask_b32_e32 v24, v225, v24, vcc
	v_lshlrev_b32_e32 v32, 16, v31
	v_and_b32_e32 v33, 0xffff0000, v31
	v_add_f32_e32 v34, v34, v38
	v_lshlrev_b32_e32 v45, 2, v24
	v_pk_mul_f32 v[24:25], v[32:33], v[32:33]
	v_add_f32_e32 v34, v35, v34
	v_add_f32_e32 v24, v24, v34
	v_add_f32_e32 v24, v25, v24
	s_mov_b32 s22, 0x800000
	s_nop 1
	v_add_f32_dpp v24, v24, v24 quad_perm:[1,0,3,2] row_mask:0xf bank_mask:0xf
	s_nop 1
	v_add_f32_dpp v24, v24, v24 quad_perm:[2,3,0,1] row_mask:0xf bank_mask:0xf
	s_nop 1
	v_add_f32_dpp v24, v24, v24 row_half_mirror row_mask:0xf bank_mask:0xf
	s_nop 1
	v_add_f32_dpp v24, v24, v24 row_mirror row_mask:0xf bank_mask:0xf
	v_fmamk_f32 v24, v24, 0x3c000000, v218
	v_mul_f32_e32 v25, 0x4b800000, v24
	v_cmp_gt_f32_e32 vcc, s22, v24
	s_nop 1
	v_cndmask_b32_e32 v24, v24, v25, vcc
	v_rsq_f32_e32 v24, v24
	s_nop 0
	v_mul_f32_e32 v25, 0x45800000, v24
	v_cndmask_b32_e32 v34, v24, v25, vcc
	v_pk_mul_f32 v[24:25], v[34:35], v[40:41] op_sel_hi:[0,1]
	v_pk_mul_f32 v[36:37], v[34:35], v[36:37] op_sel_hi:[0,1]
	v_pk_mul_f32 v[26:27], v[34:35], v[26:27] op_sel_hi:[0,1]
	v_pk_mul_f32 v[32:33], v[34:35], v[32:33] op_sel_hi:[0,1]
	v_pk_mul_f32 v[24:25], v[4:5], v[24:25]
	v_pk_mul_f32 v[36:37], v[6:7], v[36:37]
	v_pk_mul_f32 v[26:27], v[0:1], v[26:27]
	v_pk_mul_f32 v[32:33], v[2:3], v[32:33]
	v_cvt_pk_bf16_f32 v24, v24, v25
	v_cvt_pk_bf16_f32 v25, v36, v37
	v_cvt_pk_bf16_f32 v26, v26, v27
	v_cvt_pk_bf16_f32 v27, v32, v33
	s_cbranch_execnz .LBB0_611

; #define LAS __attribute__((address_space(3)))
; #define LAUNDER_V(x) asm volatile("" : "+v"(x))
; __device__ __forceinline__ unsigned pk2(float lo, float hi) { const f32x2_t f = {lo, hi}; const bf16x2_t b = __builtin_convertvector(f, bf16x2_t); return __builtin_bit_cast(unsigned, b); }
; __device__ __forceinline__ float lo16(unsigned v) { return __uint_as_float(v << 16); }
; __device__ __forceinline__ float hi16(unsigned v) { return __uint_as_float(v & 0xffff0000u); }
; __device__ __forceinline__ void stage_kv(const u16* src_base_  , int b, int L, int dil, int r, int m0, int M, LAS unsigned char* img, const float* gk, int ht) {
;     ...
;     if (!valid) { v.x = 0u; LAUNDER_V(v.x); v.y = v.x; v.z = v.x; v.w = v.x; }
;     if (gk) {
;       float f[8] = {lo16(v.x), hi16(v.x), lo16(v.y), hi16(v.y), lo16(v.z), hi16(v.z), lo16(v.w), hi16(v.w)};
;       float s = 0.f;
; #pragma unroll
;       for (int e = 0; e < 8; ++e) s += f[e] * f[e];
;       s += __shfl_xor(s, 1); s += __shfl_xor(s, 2); s += __shfl_xor(s, 4); s += __shfl_xor(s, 8);
;       const float rs = rsqrtf(s * (1.0f / 128.0f) + 1e-6f);
;       v.x = pk2(f[0] * rs * gv[0], f[1] * rs * gv[1]); v.y = pk2(f[2] * rs * gv[2], f[3] * rs * gv[3]);
;       v.z = pk2(f[4] * rs * gv[4], f[5] * rs * gv[5]); v.w = pk2(f[6] * rs * gv[6], f[7] * rs * gv[7]);
;     }
;     *(LAS u32x4*)(img + kl * KROW + dch * 16) = v;
.LBB0_613:
	s_or_saveexec_b64 s[24:25], s[24:25]
	v_mov_b32_e32 v26, v21
	v_mov_b32_e32 v27, v21
	s_xor_b64 exec, exec, s[24:25]
	v_mov_b64_e32 v[26:27], v[22:23]
	v_mov_b64_e32 v[24:25], v[20:21]
	s_or_b64 exec, exec, s[24:25]
	v_readlane_b32 s24, v253, 23
	v_readlane_b32 s25, v253, 24
	v_mov_b32_e32 v25, v21
	s_and_b64 vcc, exec, s[24:25]
	s_cbranch_vccz .LBB0_636
	v_lshlrev_b32_e32 v36, 16, v24
	v_and_b32_e32 v37, 0xffff0000, v24
	v_lshlrev_b32_e32 v32, 16, v25
	v_and_b32_e32 v33, 0xffff0000, v25
	v_pk_mul_f32 v[38:39], v[36:37], v[36:37]
	v_and_b32_e32 v21, 64, v225
	v_pk_mul_f32 v[34:35], v[32:33], v[32:33]
	v_add_f32_e32 v38, v38, v39
	v_xor_b32_e32 v20, 1, v225
	v_add_u32_e32 v40, 64, v21
	v_lshlrev_b32_e32 v22, 16, v26
	v_and_b32_e32 v23, 0xffff0000, v26
	v_add_f32_e32 v34, v34, v38
	v_cmp_lt_i32_e32 vcc, v20, v40
	v_pk_mul_f32 v[30:31], v[22:23], v[22:23]
	v_add_f32_e32 v34, v35, v34
	v_cndmask_b32_e32 v20, v225, v20, vcc
	v_lshlrev_b32_e32 v28, 16, v27
	v_and_b32_e32 v29, 0xffff0000, v27
	v_add_f32_e32 v30, v30, v34
	v_lshlrev_b32_e32 v41, 2, v20
	v_pk_mul_f32 v[20:21], v[28:29], v[28:29]
	v_add_f32_e32 v30, v31, v30
	v_add_f32_e32 v20, v20, v30
	v_add_f32_e32 v20, v21, v20
	s_mov_b32 s24, 0x800000
	s_nop 1
	v_add_f32_dpp v20, v20, v20 quad_perm:[1,0,3,2] row_mask:0xf bank_mask:0xf
	s_nop 1
	v_add_f32_dpp v20, v20, v20 quad_perm:[2,3,0,1] row_mask:0xf bank_mask:0xf
	s_nop 1
	v_add_f32_dpp v20, v20, v20 row_half_mirror row_mask:0xf bank_mask:0xf
	s_nop 1
	v_add_f32_dpp v20, v20, v20 row_mirror row_mask:0xf bank_mask:0xf
	v_fmamk_f32 v20, v20, 0x3c000000, v218
	v_mul_f32_e32 v21, 0x4b800000, v20
	v_cmp_gt_f32_e32 vcc, s24, v20
	s_nop 1
	v_cndmask_b32_e32 v20, v20, v21, vcc
	v_rsq_f32_e32 v20, v20
	s_nop 0
	v_mul_f32_e32 v21, 0x45800000, v20
	v_cndmask_b32_e32 v30, v20, v21, vcc
	v_pk_mul_f32 v[20:21], v[30:31], v[36:37] op_sel_hi:[0,1]
	v_pk_mul_f32 v[32:33], v[30:31], v[32:33] op_sel_hi:[0,1]
	v_pk_mul_f32 v[22:23], v[30:31], v[22:23] op_sel_hi:[0,1]
	v_pk_mul_f32 v[28:29], v[30:31], v[28:29] op_sel_hi:[0,1]
	v_pk_mul_f32 v[20:21], v[4:5], v[20:21]
	v_pk_mul_f32 v[32:33], v[6:7], v[32:33]
	v_pk_mul_f32 v[22:23], v[0:1], v[22:23]
	v_pk_mul_f32 v[28:29], v[2:3], v[28:29]
	v_cvt_pk_bf16_f32 v20, v20, v21
	v_cvt_pk_bf16_f32 v21, v32, v33
	v_cvt_pk_bf16_f32 v22, v22, v23
	v_cvt_pk_bf16_f32 v23, v28, v29
	s_cbranch_execnz .LBB0_618

; #define LAS __attribute__((address_space(3)))
; #define LAUNDER_V(x) asm volatile("" : "+v"(x))
; __device__ __forceinline__ unsigned pk2(float lo, float hi) { const f32x2_t f = {lo, hi}; const bf16x2_t b = __builtin_convertvector(f, bf16x2_t); return __builtin_bit_cast(unsigned, b); }
; __device__ __forceinline__ float lo16(unsigned v) { return __uint_as_float(v << 16); }
; __device__ __forceinline__ float hi16(unsigned v) { return __uint_as_float(v & 0xffff0000u); }
; __device__ __forceinline__ void stage_kv(const u16* src_base_  , int b, int L, int dil, int r, int m0, int M, LAS unsigned char* img, const float* gk, int ht) {
;     ...
;     if (!valid) { v.x = 0u; LAUNDER_V(v.x); v.y = v.x; v.z = v.x; v.w = v.x; }
;     if (gk) {
;       float f[8] = {lo16(v.x), hi16(v.x), lo16(v.y), hi16(v.y), lo16(v.z), hi16(v.z), lo16(v.w), hi16(v.w)};
;       float s = 0.f;
; #pragma unroll
;       for (int e = 0; e < 8; ++e) s += f[e] * f[e];
;       s += __shfl_xor(s, 1); s += __shfl_xor(s, 2); s += __shfl_xor(s, 4); s += __shfl_xor(s, 8);
;       const float rs = rsqrtf(s * (1.0f / 128.0f) + 1e-6f);
;       v.x = pk2(f[0] * rs * gv[0], f[1] * rs * gv[1]); v.y = pk2(f[2] * rs * gv[2], f[3] * rs * gv[3]);
;       v.z = pk2(f[4] * rs * gv[4], f[5] * rs * gv[5]); v.w = pk2(f[6] * rs * gv[6], f[7] * rs * gv[7]);
;     }
;     *(LAS u32x4*)(img + kl * KROW + dch * 16) = v;
.LBB0_620:
	s_or_saveexec_b64 s[26:27], s[26:27]
	v_mov_b32_e32 v22, v17
	v_mov_b32_e32 v23, v17
	s_xor_b64 exec, exec, s[26:27]
	v_mov_b64_e32 v[22:23], v[18:19]
	v_mov_b64_e32 v[20:21], v[16:17]
	s_or_b64 exec, exec, s[26:27]
	v_readlane_b32 s26, v253, 23
	v_readlane_b32 s27, v253, 24
	v_mov_b32_e32 v21, v17
	s_and_b64 vcc, exec, s[26:27]
	s_cbranch_vccz .LBB0_637
	v_lshlrev_b32_e32 v32, 16, v20
	v_and_b32_e32 v33, 0xffff0000, v20
	v_lshlrev_b32_e32 v28, 16, v21
	v_and_b32_e32 v29, 0xffff0000, v21
	v_pk_mul_f32 v[34:35], v[32:33], v[32:33]
	v_and_b32_e32 v17, 64, v225
	v_pk_mul_f32 v[30:31], v[28:29], v[28:29]
	v_add_f32_e32 v34, v34, v35
	v_xor_b32_e32 v16, 1, v225
	v_add_u32_e32 v36, 64, v17
	v_lshlrev_b32_e32 v18, 16, v22
	v_and_b32_e32 v19, 0xffff0000, v22
	v_add_f32_e32 v30, v30, v34
	v_cmp_lt_i32_e32 vcc, v16, v36
	v_pk_mul_f32 v[26:27], v[18:19], v[18:19]
	v_add_f32_e32 v30, v31, v30
	v_cndmask_b32_e32 v16, v225, v16, vcc
	v_lshlrev_b32_e32 v24, 16, v23
	v_and_b32_e32 v25, 0xffff0000, v23
	v_add_f32_e32 v26, v26, v30
	v_lshlrev_b32_e32 v37, 2, v16
	v_pk_mul_f32 v[16:17], v[24:25], v[24:25]
	v_add_f32_e32 v26, v27, v26
	v_add_f32_e32 v16, v16, v26
	v_add_f32_e32 v16, v17, v16
	s_mov_b32 s26, 0x800000
	s_nop 1
	v_add_f32_dpp v16, v16, v16 quad_perm:[1,0,3,2] row_mask:0xf bank_mask:0xf
	s_nop 1
	v_add_f32_dpp v16, v16, v16 quad_perm:[2,3,0,1] row_mask:0xf bank_mask:0xf
	s_nop 1
	v_add_f32_dpp v16, v16, v16 row_half_mirror row_mask:0xf bank_mask:0xf
	s_nop 1
	v_add_f32_dpp v16, v16, v16 row_mirror row_mask:0xf bank_mask:0xf
	v_fmamk_f32 v16, v16, 0x3c000000, v218
	v_mul_f32_e32 v17, 0x4b800000, v16
	v_cmp_gt_f32_e32 vcc, s26, v16
	s_mov_b64 s[26:27], 0
	s_nop 0
	v_cndmask_b32_e32 v16, v16, v17, vcc
	v_rsq_f32_e32 v16, v16
	s_nop 0
	v_mul_f32_e32 v17, 0x45800000, v16
	v_cndmask_b32_e32 v26, v16, v17, vcc
	v_pk_mul_f32 v[16:17], v[26:27], v[32:33] op_sel_hi:[0,1]
	v_pk_mul_f32 v[28:29], v[26:27], v[28:29] op_sel_hi:[0,1]
	v_pk_mul_f32 v[18:19], v[26:27], v[18:19] op_sel_hi:[0,1]
	v_pk_mul_f32 v[24:25], v[26:27], v[24:25] op_sel_hi:[0,1]
	v_pk_mul_f32 v[16:17], v[4:5], v[16:17]
	v_pk_mul_f32 v[28:29], v[6:7], v[28:29]
	v_pk_mul_f32 v[18:19], v[0:1], v[18:19]
	v_pk_mul_f32 v[24:25], v[2:3], v[24:25]
	v_cvt_pk_bf16_f32 v16, v16, v17
	v_cvt_pk_bf16_f32 v17, v28, v29
	v_cvt_pk_bf16_f32 v18, v18, v19
	v_cvt_pk_bf16_f32 v19, v24, v25
	s_branch .LBB0_638

; __device__ __forceinline__ unsigned pk2(float lo, float hi) { const f32x2_t f = {lo, hi}; const bf16x2_t b = __builtin_convertvector(f, bf16x2_t); return __builtin_bit_cast(unsigned, b); }
; __device__ __forceinline__ float lo16(unsigned v) { return __uint_as_float(v << 16); }
; __device__ __forceinline__ float hi16(unsigned v) { return __uint_as_float(v & 0xffff0000u); }
; __device__ __forceinline__ void stage_kv(const u16* src_base_  , int b, int L, int dil, int r, int m0, int M, LAS unsigned char* img, const float* gk, int ht) {
;     ...
;       float f[8] = {lo16(v.x), hi16(v.x), lo16(v.y), hi16(v.y), lo16(v.z), hi16(v.z), lo16(v.w), hi16(v.w)};
;       float s = 0.f;
; #pragma unroll
;       for (int e = 0; e < 8; ++e) s += f[e] * f[e];
;       s += __shfl_xor(s, 1); s += __shfl_xor(s, 2); s += __shfl_xor(s, 4); s += __shfl_xor(s, 8);
;       const float rs = rsqrtf(s * (1.0f / 128.0f) + 1e-6f);
;       v.x = pk2(f[0] * rs * gv[0], f[1] * rs * gv[1]); v.y = pk2(f[2] * rs * gv[2], f[3] * rs * gv[3]);
;       v.z = pk2(f[4] * rs * gv[4], f[5] * rs * gv[5]); v.w = pk2(f[6] * rs * gv[6], f[7] * rs * gv[7]);
.LBB0_642:
	s_or_saveexec_b64 s[28:29], s[28:29]
	v_mov_b32_e32 v18, v13
	v_mov_b32_e32 v19, v13
	s_xor_b64 exec, exec, s[28:29]
	v_mov_b64_e32 v[18:19], v[14:15]
	v_mov_b64_e32 v[16:17], v[12:13]
	s_or_b64 exec, exec, s[28:29]
	v_readlane_b32 s28, v253, 23
	v_readlane_b32 s29, v253, 24
	v_mov_b32_e32 v17, v13
	s_and_b64 vcc, exec, s[28:29]
	s_cbranch_vccz .LBB0_646
	v_lshlrev_b32_e32 v28, 16, v16
	v_and_b32_e32 v29, 0xffff0000, v16
	v_lshlrev_b32_e32 v24, 16, v17
	v_and_b32_e32 v25, 0xffff0000, v17
	v_pk_mul_f32 v[30:31], v[28:29], v[28:29]
	v_and_b32_e32 v13, 64, v225
	v_pk_mul_f32 v[26:27], v[24:25], v[24:25]
	v_add_f32_e32 v30, v30, v31
	v_xor_b32_e32 v12, 1, v225
	v_add_u32_e32 v32, 64, v13
	v_lshlrev_b32_e32 v14, 16, v18
	v_and_b32_e32 v15, 0xffff0000, v18
	v_add_f32_e32 v26, v26, v30
	v_cmp_lt_i32_e32 vcc, v12, v32
	v_pk_mul_f32 v[22:23], v[14:15], v[14:15]
	v_add_f32_e32 v26, v27, v26
	v_cndmask_b32_e32 v12, v225, v12, vcc
	v_lshlrev_b32_e32 v20, 16, v19
	v_and_b32_e32 v21, 0xffff0000, v19
	v_add_f32_e32 v22, v22, v26
	v_lshlrev_b32_e32 v33, 2, v12
	v_pk_mul_f32 v[12:13], v[20:21], v[20:21]
	v_add_f32_e32 v22, v23, v22
	v_add_f32_e32 v12, v12, v22
	v_add_f32_e32 v12, v13, v12
	s_mov_b32 s28, 0x800000
	s_nop 1
	v_add_f32_dpp v12, v12, v12 quad_perm:[1,0,3,2] row_mask:0xf bank_mask:0xf
	s_nop 1
	v_add_f32_dpp v12, v12, v12 quad_perm:[2,3,0,1] row_mask:0xf bank_mask:0xf
	s_nop 1
	v_add_f32_dpp v12, v12, v12 row_half_mirror row_mask:0xf bank_mask:0xf
	s_nop 1
	v_add_f32_dpp v12, v12, v12 row_mirror row_mask:0xf bank_mask:0xf
	v_fmamk_f32 v12, v12, 0x3c000000, v218
	v_mul_f32_e32 v13, 0x4b800000, v12
	v_cmp_gt_f32_e32 vcc, s28, v12
	s_mov_b64 s[28:29], 0
	s_nop 0
	v_cndmask_b32_e32 v12, v12, v13, vcc
	v_rsq_f32_e32 v12, v12
	s_nop 0
	v_mul_f32_e32 v13, 0x45800000, v12
	v_cndmask_b32_e32 v22, v12, v13, vcc
	v_pk_mul_f32 v[12:13], v[22:23], v[28:29] op_sel_hi:[0,1]
	v_pk_mul_f32 v[24:25], v[22:23], v[24:25] op_sel_hi:[0,1]
	v_pk_mul_f32 v[14:15], v[22:23], v[14:15] op_sel_hi:[0,1]
	v_pk_mul_f32 v[20:21], v[22:23], v[20:21] op_sel_hi:[0,1]
	v_pk_mul_f32 v[12:13], v[4:5], v[12:13]
	v_pk_mul_f32 v[24:25], v[6:7], v[24:25]
	v_pk_mul_f32 v[14:15], v[0:1], v[14:15]
	v_pk_mul_f32 v[20:21], v[2:3], v[20:21]
	v_cvt_pk_bf16_f32 v12, v12, v13
	v_cvt_pk_bf16_f32 v13, v24, v25
	v_cvt_pk_bf16_f32 v14, v14, v15
	v_cvt_pk_bf16_f32 v15, v20, v21
	s_branch .LBB0_647

; __device__ __forceinline__ unsigned pk2(float lo, float hi) { const f32x2_t f = {lo, hi}; const bf16x2_t b = __builtin_convertvector(f, bf16x2_t); return __builtin_bit_cast(unsigned, b); }
; __device__ __forceinline__ float lo16(unsigned v) { return __uint_as_float(v << 16); }
; __device__ __forceinline__ float hi16(unsigned v) { return __uint_as_float(v & 0xffff0000u); }
; __device__ __forceinline__ void stage_kv(const u16* src_base_  , int b, int L, int dil, int r, int m0, int M, LAS unsigned char* img, const float* gk, int ht) {
;     ...
;       float f[8] = {lo16(v.x), hi16(v.x), lo16(v.y), hi16(v.y), lo16(v.z), hi16(v.z), lo16(v.w), hi16(v.w)};
;       float s = 0.f;
; #pragma unroll
;       for (int e = 0; e < 8; ++e) s += f[e] * f[e];
;       s += __shfl_xor(s, 1); s += __shfl_xor(s, 2); s += __shfl_xor(s, 4); s += __shfl_xor(s, 8);
;       const float rs = rsqrtf(s * (1.0f / 128.0f) + 1e-6f);
;       v.x = pk2(f[0] * rs * gv[0], f[1] * rs * gv[1]); v.y = pk2(f[2] * rs * gv[2], f[3] * rs * gv[3]);
;       v.z = pk2(f[4] * rs * gv[4], f[5] * rs * gv[5]); v.w = pk2(f[6] * rs * gv[6], f[7] * rs * gv[7]);
.LBB0_651:
	s_or_saveexec_b64 s[92:93], s[92:93]
	v_mov_b32_e32 v14, v9
	v_mov_b32_e32 v15, v9
	s_xor_b64 exec, exec, s[92:93]
	v_mov_b64_e32 v[14:15], v[10:11]
	v_mov_b64_e32 v[12:13], v[8:9]
	s_or_b64 exec, exec, s[92:93]
	v_readlane_b32 s78, v253, 23
	v_readlane_b32 s79, v253, 24
	v_mov_b32_e32 v13, v9
	s_and_b64 vcc, exec, s[78:79]
	s_cbranch_vccz .LBB0_884
	v_lshlrev_b32_e32 v24, 16, v12
	v_and_b32_e32 v25, 0xffff0000, v12
	v_and_b32_e32 v9, 64, v225
	v_lshlrev_b32_e32 v20, 16, v13
	v_and_b32_e32 v21, 0xffff0000, v13
	v_pk_mul_f32 v[26:27], v[24:25], v[24:25]
	v_xor_b32_e32 v8, 1, v225
	v_add_u32_e32 v28, 64, v9
	v_pk_mul_f32 v[22:23], v[20:21], v[20:21]
	v_add_f32_e32 v26, v26, v27
	v_cmp_lt_i32_e32 vcc, v8, v28
	v_lshlrev_b32_e32 v16, 16, v14
	v_and_b32_e32 v17, 0xffff0000, v14
	v_add_f32_e32 v22, v22, v26
	v_cndmask_b32_e32 v8, v225, v8, vcc
	v_pk_mul_f32 v[18:19], v[16:17], v[16:17]
	v_add_f32_e32 v22, v23, v22
	v_lshlrev_b32_e32 v29, 2, v8
	v_lshlrev_b32_e32 v8, 16, v15
	v_and_b32_e32 v9, 0xffff0000, v15
	v_add_f32_e32 v18, v18, v22
	v_pk_mul_f32 v[10:11], v[8:9], v[8:9]
	v_add_f32_e32 v18, v19, v18
	v_add_f32_e32 v10, v10, v18
	v_add_f32_e32 v10, v11, v10
	s_mov_b32 s77, 0x800000
	s_nop 1
	v_add_f32_dpp v10, v10, v10 quad_perm:[1,0,3,2] row_mask:0xf bank_mask:0xf
	s_nop 1
	v_add_f32_dpp v10, v10, v10 quad_perm:[2,3,0,1] row_mask:0xf bank_mask:0xf
	s_nop 1
	v_add_f32_dpp v10, v10, v10 row_half_mirror row_mask:0xf bank_mask:0xf
	s_nop 1
	v_add_f32_dpp v10, v10, v10 row_mirror row_mask:0xf bank_mask:0xf
	v_fmamk_f32 v10, v10, 0x3c000000, v218
	v_mul_f32_e32 v11, 0x4b800000, v10
	v_cmp_gt_f32_e32 vcc, s77, v10
	s_nop 1
	v_cndmask_b32_e32 v10, v10, v11, vcc
	v_rsq_f32_e32 v10, v10
	s_nop 0
	v_mul_f32_e32 v11, 0x45800000, v10
	v_cndmask_b32_e32 v10, v10, v11, vcc
	v_pk_mul_f32 v[18:19], v[10:11], v[24:25] op_sel_hi:[0,1]
	v_pk_mul_f32 v[4:5], v[4:5], v[18:19]
	v_pk_mul_f32 v[18:19], v[10:11], v[20:21] op_sel_hi:[0,1]
	v_pk_mul_f32 v[6:7], v[6:7], v[18:19]
	v_cvt_pk_bf16_f32 v4, v4, v5
	v_cvt_pk_bf16_f32 v5, v6, v7
	v_pk_mul_f32 v[6:7], v[10:11], v[16:17] op_sel_hi:[0,1]
	v_pk_mul_f32 v[0:1], v[0:1], v[6:7]
	s_nop 0
	v_cvt_pk_bf16_f32 v6, v0, v1
	v_pk_mul_f32 v[0:1], v[10:11], v[8:9] op_sel_hi:[0,1]
	v_pk_mul_f32 v[0:1], v[2:3], v[0:1]
	s_nop 0
	v_cvt_pk_bf16_f32 v7, v0, v1
	s_cbranch_execnz .LBB0_656
